# P3, P5, P8 hand-written residual epilogues writing h1/h2/h3 to padded-stride (8320B) buffers in dead workspace regions; P4 A operand, int8 row-quant pass and P9 read the padded buffers
# speedup vs baseline: 1.0054x; 1.0012x over previous
; #define GAS __attribute__((address_space(1)))
; #define LAS __attribute__((address_space(3)))
; template <int MAP> __device__ __forceinline__ void quant_strip(const float* W, int N, unsigned char* W8, const float* gk, unsigned* cmax, LAS unsigned char* lds, int strip, int wave, int lane) {
;     LAS float* smax = (LAS float*)(lds + 8 * 16896);
;     const int n0 = 32 * strip, n4 = lane & 7, kr = lane >> 3;
;     f32x4 mx = (f32x4){0.f, 0.f, 0.f, 0.f};
; #pragma unroll 16
;     for (int i = 0; i < 64; ++i) { const int k = 512 * wave + 8 * i + kr; const f32x4 v = *(const GAS f32x4*)(W + (size_t)k * N + n0 + 4 * n4) * gk[k];
;         mx[0] = fmaxf(mx[0], fabsf(v[0])); mx[1] = fmaxf(mx[1], fabsf(v[1])); mx[2] = fmaxf(mx[2], fabsf(v[2])); mx[3] = fmaxf(mx[3], fabsf(v[3])); }
; #pragma unroll
;     for (int e = 0; e < 4; ++e) { mx[e] = fmaxf(mx[e], __shfl_xor(mx[e], 8)); mx[e] = fmaxf(mx[e], __shfl_xor(mx[e], 16)); mx[e] = fmaxf(mx[e], __shfl_xor(mx[e], 32)); }
;     if (kr == 0) *(LAS f32x4*)(smax + wave * 32 + 4 * n4) = mx;
;     __syncthreads();
;     if (wave == 0 && lane < 32) { float m = 0.f;
; __global__ void __launch_bounds__(NWAVES * 64, 2) fwd_kernel(Args args) {
;     ...
;     if (IN(3)) {
;         pg8::Gemm g{MIX, WOUT, DM, DM, DM, 1, 1 << 30, 0, 0, 0, 0, 0}; pg8::StaticOrder S; S.init(MTOK / 256, DM / 256, G, bx);
;         constexpr int I_Q8 = (DM / 128) * (FF / 32); const int hq = G >> 1;
;         if ((bx & 1) && hq > 0) { LAS float* qscr = (LAS float*)(lds + wave * 16896);
;             (void)qscr; for (int st = (bx >> 1); st < FF / 32; st += hq) quant_strip<2>(w_gate, FF, WGU8, g_ffn, cmaxU, lds, st, wave, lane);
.LBB0_762:
	v_readlane_b32 s36, v244, 2
	v_readlane_b32 s50, v244, 16
	v_readlane_b32 s51, v244, 17
	s_add_u32 s0, s50, 0x17100000
	s_addc_u32 s1, s51, 0
	s_add_u32 s98, s50, 0x1c700000
	s_addc_u32 s99, s51, 0
	s_add_u32 s52, s50, 0x2b500000
	v_readlane_b32 s37, v244, 3
	v_readlane_b32 s38, v244, 4
	v_readlane_b32 s39, v244, 5
	v_readlane_b32 s40, v244, 6
	v_readlane_b32 s41, v244, 7
	v_readlane_b32 s42, v244, 8
	v_readlane_b32 s43, v244, 9
	v_readlane_b32 s44, v244, 10
	v_readlane_b32 s45, v244, 11
	v_readlane_b32 s46, v244, 12
	v_readlane_b32 s47, v244, 13
	v_readlane_b32 s48, v244, 14
	v_readlane_b32 s49, v244, 15
	v_writelane_b32 v244, s0, 49
	s_addc_u32 s53, s51, 0
	s_nop 0
	v_writelane_b32 v244, s1, 50
	s_add_u32 s0, s50, 0x70000
	s_addc_u32 s1, s51, 0
	s_add_u32 s62, s50, 0x40000
	s_addc_u32 s63, s51, 0
	v_writelane_b32 v244, s0, 23
	s_cmp_lt_i32 s96, 4
	s_nop 0
	v_writelane_b32 v244, s1, 24
	s_cselect_b64 s[0:1], -1, 0
	s_cmp_gt_i32 s97, 3
	s_cselect_b64 s[2:3], -1, 0
	s_and_b64 s[0:1], s[0:1], s[2:3]
	s_andn2_b64 vcc, exec, s[0:1]
	s_cbranch_vccnz .LBB0_873
	s_ashr_i32 s23, s22, 1
	s_and_b32 s56, s16, 1
	s_cmp_eq_u32 s56, 0
	s_cselect_b64 s[0:1], -1, 0
	s_cmp_gt_i32 s23, 0
	s_cselect_b64 s[54:55], -1, 0
	s_cmp_lt_i32 s23, 1
	s_cselect_b64 s[2:3], -1, 0
	s_or_b64 s[0:1], s[0:1], s[2:3]
	s_and_b64 vcc, exec, s[0:1]
	s_cbranch_vccnz .LBB0_776
	s_ashr_i32 s14, s16, 1
	s_cmpk_gt_i32 s14, 0x157
	s_cbranch_scc1 .LBB0_775
	s_waitcnt vmcnt(47)
	v_lshlrev_b32_e32 v2, 4, v0
	v_readlane_b32 s36, v244, 2
	v_and_b32_e32 v2, 0x70, v2
	v_mov_b32_e32 v3, 0
	v_readlane_b32 s38, v244, 4
	v_readlane_b32 s39, v244, 5
	v_readlane_b32 s6, v244, 42
	s_lshl_b32 s0, s6, 7
	v_lshl_add_u64 v[4:5], s[38:39], 0, v[2:3]
	v_mbcnt_lo_u32_b32 v2, -1, 0
	v_mbcnt_hi_u32_b32 v2, -1, v2
	s_waitcnt vmcnt(46)
	v_and_b32_e32 v7, 64, v2
	v_xor_b32_e32 v6, 8, v2
	v_add_u32_e32 v7, 64, v7
	v_cmp_lt_i32_e32 vcc, v6, v7
	s_add_i32 s4, 0, 0x21000
	s_add_i32 s5, s4, s0
	v_cndmask_b32_e32 v6, v2, v6, vcc
	s_waitcnt vmcnt(41)
	v_lshlrev_b32_e32 v19, 2, v6
	v_xor_b32_e32 v6, 16, v2
	v_cmp_lt_i32_e32 vcc, v6, v7
	v_readlane_b32 s7, v244, 41
	v_and_b32_e32 v1, 63, v0
	v_cndmask_b32_e32 v6, v2, v6, vcc
	v_lshlrev_b32_e32 v20, 2, v6
	v_xor_b32_e32 v6, 32, v2
	v_cmp_lt_i32_e32 vcc, v6, v7
	s_cmp_lt_u32 s7, 64
	s_cselect_b64 s[0:1], -1, 0
	v_cndmask_b32_e32 v2, v2, v6, vcc
	v_cmp_gt_u32_e32 vcc, 32, v1
	s_and_b64 s[8:9], s[0:1], vcc
	s_cmpk_lt_u32 s7, 0x800
	s_mul_i32 s0, s6, 0x4200
	v_and_b32_e32 v8, 7, v0
	v_readlane_b32 s24, v244, 49
	v_bfe_u32 v18, v0, 3, 3
	v_lshlrev_b32_e32 v21, 2, v2
	s_cselect_b64 s[10:11], -1, 0
	s_add_i32 s0, s0, 0
	v_lshlrev_b32_e32 v2, 4, v8
	v_readlane_b32 s25, v244, 50
	v_lshl_add_u64 v[6:7], s[38:39], 0, v[2:3]
	v_add_u32_e32 v11, s0, v2
	v_mul_u32_u24_e32 v13, 0x840, v8
	v_lshl_add_u64 v[8:9], s[24:25], 0, v[2:3]
	v_lshlrev_b32_e32 v2, 2, v18
	v_lshlrev_b32_e32 v10, 4, v1
	v_mul_u32_u24_e32 v12, 0x84, v18
	s_waitcnt vmcnt(40)
	v_or_b32_e32 v23, 8, v18
	v_or_b32_e32 v24, 16, v18
	v_or_b32_e32 v25, 24, v18
	s_add_i32 s1, 0, 0x21400
	s_waitcnt vmcnt(39)
	v_add3_u32 v27, s0, v13, v2
	s_mul_i32 s0, s6, 0x158
	v_cmp_gt_u32_e64 s[2:3], 8, v1
	v_lshl_add_u32 v22, v1, 2, s4
	v_add_u32_e32 v26, s1, v2
	v_lshl_add_u32 v28, v23, 2, s1
	v_lshl_add_u32 v29, v24, 2, s1
	v_lshl_add_u32 v30, v25, 2, s1
	v_lshl_or_b32 v31, s6, 9, v18
	s_add_i32 s15, s6, -8
	s_add_i32 s17, s14, s0
	s_mov_b32 s19, 0xac00
	v_add_u32_e32 v32, s5, v10
	v_add_u32_e32 v33, v11, v12
	s_mov_b32 s24, 0x42fe0000
	s_mov_b32 s25, 0xc2fe0000
	s_mov_b32 s26, 0x40c0c00
	s_waitcnt vmcnt(38)
	v_mov_b32_e32 v34, 0x42fe0000
	v_readlane_b32 s37, v244, 3
	v_readlane_b32 s40, v244, 6
	v_readlane_b32 s41, v244, 7
	v_readlane_b32 s42, v244, 8
	v_readlane_b32 s43, v244, 9
	v_readlane_b32 s44, v244, 10
	v_readlane_b32 s45, v244, 11
	v_readlane_b32 s46, v244, 12
	v_readlane_b32 s47, v244, 13
	v_readlane_b32 s48, v244, 14
	v_readlane_b32 s49, v244, 15
	v_readlane_b32 s50, v244, 16
	v_readlane_b32 s51, v244, 17
	s_branch .LBB0_767

; __device__ __forceinline__ unsigned cvt_pk_bf16(float lo, float hi) { unsigned r; asm volatile("v_cvt_pk_bf16_f32 %0, %1, %2" : "=v"(r) : "v"(lo), "v"(hi)); return r; }
; __device__ __forceinline__ float bf_lo(unsigned w) { return __uint_as_float(w << 16); }
; __device__ __forceinline__ float bf_hi(unsigned w) { return __uint_as_float(w & 0xffff0000u); }
;     __device__ __forceinline__ void operator()(EPI_ARGS) const {
;     ...
;                 for (int bj = 0; bj < 2; ++bj) { const size_t off = (size_t)(row0 + ai * HALF + m * 16) * ldc + col0 + bj * HALF;
;                     if (RES_BF16) { const u32x4 rw = *(const u32x4*)((const bf16*)resid + off); r0[m][bj] = __builtin_bit_cast(f32x4, rw); }
;                     else { r0[m][bj] = *(const f32x4*)((const float*)resid + off); r1[m][bj] = *(const f32x4*)((const float*)resid + off + 4); } }
; #pragma unroll
;             for (int m = 0; m < 4; ++m) { const int row = row0 + ai * HALF + m * 16; const size_t off = (size_t)row * ldc + col0; float ss = 0.f, mx = 0.f;
; #pragma unroll
;                 for (int bj = 0; bj < 2; ++bj) {
;                     f32x4 a0, a1;
;                     if (RES_BF16) { const u32x4 rw = __builtin_bit_cast(u32x4, r0[m][bj]); a0 = (f32x4){bf_lo(rw.x), bf_hi(rw.x), bf_lo(rw.y), bf_hi(rw.y)}; a1 = (f32x4){bf_lo(rw.z), bf_hi(rw.z), bf_lo(rw.w), bf_hi(rw.w)};
;                         if (RES_SCALE) { const float rf = rfac[row]; a0 = a0 * rf; a1 = a1 * rf; } }
;                     else { a0 = r0[m][bj]; a1 = r1[m][bj]; }
;                     const f32x4 v0 = acc[ai][bj][m][0] + a0, v1 = acc[ai][bj][m][1] + a1;
;                     u32x4 w; w.x = cvt_pk_bf16(v0[0], v0[1]); w.y = cvt_pk_bf16(v0[2], v0[3]); w.z = cvt_pk_bf16(v1[0], v1[1]); w.w = cvt_pk_bf16(v1[2], v1[3]); *(u32x4*)(ob + off + bj * HALF) = w;
;                     ss += (v0[0] * v0[0] + v0[1] * v0[1]) + (v0[2] * v0[2] + v0[3] * v0[3]) + (v1[0] * v1[0] + v1[1] * v1[1]) + (v1[2] * v1[2] + v1[3] * v1[3]);
;                     if (rowmax) mx = fmaxf(mx, fmaxf(fmaxf(fmaxf(fabsf(v0[0]), fabsf(v0[1])), fmaxf(fabsf(v0[2]), fabsf(v0[3]))), fmaxf(fmaxf(fabsf(v1[0]), fabsf(v1[1])), fmaxf(fabsf(v1[2]), fabsf(v1[3]))))); }
.LBB0_792:
	s_nop 7
	v_lshl_add_u32 v252, s78, 8, v189
	v_lshlrev_b32_e32 v252, 2, v252
	global_load_dword v214, v252, s[66:67]
	global_load_dword v216, v252, s[66:67] offset:64
	global_load_dword v218, v252, s[66:67] offset:128
	global_load_dword v220, v252, s[66:67] offset:192
	global_load_dword v222, v252, s[66:67] offset:512
	global_load_dword v224, v252, s[66:67] offset:576
	global_load_dword v226, v252, s[66:67] offset:640
	global_load_dword v228, v252, s[66:67] offset:704
	v_lshl_add_u32 v245, s78, 8, v189
	v_lshlrev_b32_e32 v245, 13, v245
	v_lshl_or_b32 v246, s24, 8, v190
	v_lshl_add_u32 v245, v246, 1, v245
	global_load_dwordx4 v[98:101], v245, s[12:13]
	global_load_dwordx4 v[110:113], v245, s[12:13] offset:256
	v_add_u32_e32 v246, 0x20000, v245
	global_load_dwordx4 v[122:125], v246, s[12:13]
	global_load_dwordx4 v[134:137], v246, s[12:13] offset:256
	v_add_u32_e32 v255, 0x40000, v245
	global_load_dwordx4 v[138:141], v255, s[12:13]
	global_load_dwordx4 v[150:153], v255, s[12:13] offset:256
	v_add_u32_e32 v246, 0x60000, v245
	global_load_dwordx4 v[154:157], v246, s[12:13]
	global_load_dwordx4 v[162:165], v246, s[12:13] offset:256
	v_add_u32_e32 v255, 0x100000, v245
	global_load_dwordx4 v[166:169], v255, s[12:13]
	global_load_dwordx4 v[170:173], v255, s[12:13] offset:256
	v_add_u32_e32 v246, 0x120000, v245
	global_load_dwordx4 v[174:177], v246, s[12:13]
	global_load_dwordx4 v[178:181], v246, s[12:13] offset:256
	v_add_u32_e32 v255, 0x140000, v245
	global_load_dwordx4 v[198:201], v255, s[12:13]
	global_load_dwordx4 v[202:205], v255, s[12:13] offset:256
	v_add_u32_e32 v246, 0x160000, v245
	global_load_dwordx4 v[206:209], v246, s[12:13]
	global_load_dwordx4 v[210:213], v246, s[12:13] offset:256
	v_lshl_add_u32 v245, s78, 8, v189
	v_mul_u32_u24_e32 v245, 0x2080, v245
	v_lshl_or_b32 v246, s24, 8, v190
	v_lshl_add_u32 v245, v246, 1, v245
	s_waitcnt vmcnt(15)
	v_lshlrev_b32_e32 v248, 16, v98
	v_and_b32_e32 v249, 0xffff0000, v98
	v_lshlrev_b32_e32 v250, 16, v99
	v_and_b32_e32 v251, 0xffff0000, v99
	v_pk_fma_f32 v[146:147], v[214:215], v[248:249], v[146:147] op_sel_hi:[0,1,1]
	v_pk_fma_f32 v[148:149], v[214:215], v[250:251], v[148:149] op_sel_hi:[0,1,1]
	v_lshlrev_b32_e32 v248, 16, v100
	v_and_b32_e32 v249, 0xffff0000, v100
	v_lshlrev_b32_e32 v250, 16, v101
	v_and_b32_e32 v251, 0xffff0000, v101
	v_pk_fma_f32 v[142:143], v[214:215], v[248:249], v[142:143] op_sel_hi:[0,1,1]
	v_pk_fma_f32 v[144:145], v[214:215], v[250:251], v[144:145] op_sel_hi:[0,1,1]
	v_cvt_pk_bf16_f32 v98, v146, v147
	v_cvt_pk_bf16_f32 v99, v148, v149
	v_cvt_pk_bf16_f32 v100, v142, v143
	v_cvt_pk_bf16_f32 v101, v144, v145
	global_store_dwordx4 v245, v[98:101], s[98:99]
	v_mul_f32_e32 v247, v146, v146
	v_fmac_f32_e32 v247, v147, v147
	v_fmac_f32_e32 v247, v148, v148
	v_fmac_f32_e32 v247, v149, v149
	v_mul_f32_e32 v254, v142, v142
	v_fmac_f32_e32 v254, v143, v143
	v_fmac_f32_e32 v254, v144, v144
	v_fmac_f32_e32 v254, v145, v145
	s_waitcnt vmcnt(15)
	v_lshlrev_b32_e32 v248, 16, v110
	v_and_b32_e32 v249, 0xffff0000, v110
	v_lshlrev_b32_e32 v250, 16, v111
	v_and_b32_e32 v251, 0xffff0000, v111
	v_pk_fma_f32 v[130:131], v[214:215], v[248:249], v[130:131] op_sel_hi:[0,1,1]
	v_pk_fma_f32 v[132:133], v[214:215], v[250:251], v[132:133] op_sel_hi:[0,1,1]
	v_lshlrev_b32_e32 v248, 16, v112
	v_and_b32_e32 v249, 0xffff0000, v112
	v_lshlrev_b32_e32 v250, 16, v113
	v_and_b32_e32 v251, 0xffff0000, v113
	v_pk_fma_f32 v[126:127], v[214:215], v[248:249], v[126:127] op_sel_hi:[0,1,1]
	v_pk_fma_f32 v[128:129], v[214:215], v[250:251], v[128:129] op_sel_hi:[0,1,1]
	v_cvt_pk_bf16_f32 v110, v130, v131
	v_cvt_pk_bf16_f32 v111, v132, v133
	v_cvt_pk_bf16_f32 v112, v126, v127
	v_cvt_pk_bf16_f32 v113, v128, v129
	global_store_dwordx4 v245, v[110:113], s[98:99] offset:256
	v_fmac_f32_e32 v247, v130, v130
	v_fmac_f32_e32 v247, v131, v131
	v_fmac_f32_e32 v247, v132, v132
	v_fmac_f32_e32 v247, v133, v133
	v_fmac_f32_e32 v254, v126, v126
	v_fmac_f32_e32 v254, v127, v127
	v_fmac_f32_e32 v254, v128, v128
	v_fmac_f32_e32 v254, v129, v129
	v_add_f32_e32 v146, v247, v254
	s_waitcnt vmcnt(15)
	v_lshlrev_b32_e32 v248, 16, v122
	v_and_b32_e32 v249, 0xffff0000, v122
	v_lshlrev_b32_e32 v250, 16, v123
	v_and_b32_e32 v251, 0xffff0000, v123
	v_pk_fma_f32 v[118:119], v[216:217], v[248:249], v[118:119] op_sel_hi:[0,1,1]
	v_pk_fma_f32 v[120:121], v[216:217], v[250:251], v[120:121] op_sel_hi:[0,1,1]
	v_lshlrev_b32_e32 v248, 16, v124
	v_and_b32_e32 v249, 0xffff0000, v124
	v_lshlrev_b32_e32 v250, 16, v125
	v_and_b32_e32 v251, 0xffff0000, v125
	v_pk_fma_f32 v[114:115], v[216:217], v[248:249], v[114:115] op_sel_hi:[0,1,1]
	v_pk_fma_f32 v[116:117], v[216:217], v[250:251], v[116:117] op_sel_hi:[0,1,1]
	v_cvt_pk_bf16_f32 v122, v118, v119
	v_cvt_pk_bf16_f32 v123, v120, v121
	v_cvt_pk_bf16_f32 v124, v114, v115
	v_cvt_pk_bf16_f32 v125, v116, v117
	v_add_u32_e32 v246, 0x20800, v245
	global_store_dwordx4 v246, v[122:125], s[98:99]
	v_mul_f32_e32 v247, v118, v118
	v_fmac_f32_e32 v247, v119, v119
	v_fmac_f32_e32 v247, v120, v120
	v_fmac_f32_e32 v247, v121, v121
	v_mul_f32_e32 v254, v114, v114
	v_fmac_f32_e32 v254, v115, v115
	v_fmac_f32_e32 v254, v116, v116
	v_fmac_f32_e32 v254, v117, v117
	s_waitcnt vmcnt(15)
; __device__ __forceinline__ unsigned cvt_pk_bf16(float lo, float hi) { unsigned r; asm volatile("v_cvt_pk_bf16_f32 %0, %1, %2" : "=v"(r) : "v"(lo), "v"(hi)); return r; }
; __device__ __forceinline__ float bf_lo(unsigned w) { return __uint_as_float(w << 16); }
; __device__ __forceinline__ float bf_hi(unsigned w) { return __uint_as_float(w & 0xffff0000u); }
;     __device__ __forceinline__ void operator()(EPI_ARGS) const {
;     ...
;                 for (int bj = 0; bj < 2; ++bj) { const size_t off = (size_t)(row0 + ai * HALF + m * 16) * ldc + col0 + bj * HALF;
;                     if (RES_BF16) { const u32x4 rw = *(const u32x4*)((const bf16*)resid + off); r0[m][bj] = __builtin_bit_cast(f32x4, rw); }
;                     else { r0[m][bj] = *(const f32x4*)((const float*)resid + off); r1[m][bj] = *(const f32x4*)((const float*)resid + off + 4); } }
; #pragma unroll
;             for (int m = 0; m < 4; ++m) { const int row = row0 + ai * HALF + m * 16; const size_t off = (size_t)row * ldc + col0; float ss = 0.f, mx = 0.f;
; #pragma unroll
;                 for (int bj = 0; bj < 2; ++bj) {
;                     f32x4 a0, a1;
;                     if (RES_BF16) { const u32x4 rw = __builtin_bit_cast(u32x4, r0[m][bj]); a0 = (f32x4){bf_lo(rw.x), bf_hi(rw.x), bf_lo(rw.y), bf_hi(rw.y)}; a1 = (f32x4){bf_lo(rw.z), bf_hi(rw.z), bf_lo(rw.w), bf_hi(rw.w)};
;                         if (RES_SCALE) { const float rf = rfac[row]; a0 = a0 * rf; a1 = a1 * rf; } }
;                     else { a0 = r0[m][bj]; a1 = r1[m][bj]; }
;                     const f32x4 v0 = acc[ai][bj][m][0] + a0, v1 = acc[ai][bj][m][1] + a1;
;                     u32x4 w; w.x = cvt_pk_bf16(v0[0], v0[1]); w.y = cvt_pk_bf16(v0[2], v0[3]); w.z = cvt_pk_bf16(v1[0], v1[1]); w.w = cvt_pk_bf16(v1[2], v1[3]); *(u32x4*)(ob + off + bj * HALF) = w;
;                     ss += (v0[0] * v0[0] + v0[1] * v0[1]) + (v0[2] * v0[2] + v0[3] * v0[3]) + (v1[0] * v1[0] + v1[1] * v1[1]) + (v1[2] * v1[2] + v1[3] * v1[3]);
;                     if (rowmax) mx = fmaxf(mx, fmaxf(fmaxf(fmaxf(fabsf(v0[0]), fabsf(v0[1])), fmaxf(fabsf(v0[2]), fabsf(v0[3]))), fmaxf(fmaxf(fabsf(v1[0]), fabsf(v1[1])), fmaxf(fabsf(v1[2]), fabsf(v1[3]))))); }
	v_lshlrev_b32_e32 v248, 16, v134
	v_and_b32_e32 v249, 0xffff0000, v134
	v_lshlrev_b32_e32 v250, 16, v135
	v_and_b32_e32 v251, 0xffff0000, v135
	v_pk_fma_f32 v[106:107], v[216:217], v[248:249], v[106:107] op_sel_hi:[0,1,1]
	v_pk_fma_f32 v[108:109], v[216:217], v[250:251], v[108:109] op_sel_hi:[0,1,1]
	v_lshlrev_b32_e32 v248, 16, v136
	v_and_b32_e32 v249, 0xffff0000, v136
	v_lshlrev_b32_e32 v250, 16, v137
	v_and_b32_e32 v251, 0xffff0000, v137
	v_pk_fma_f32 v[102:103], v[216:217], v[248:249], v[102:103] op_sel_hi:[0,1,1]
	v_pk_fma_f32 v[104:105], v[216:217], v[250:251], v[104:105] op_sel_hi:[0,1,1]
	v_cvt_pk_bf16_f32 v134, v106, v107
	v_cvt_pk_bf16_f32 v135, v108, v109
	v_cvt_pk_bf16_f32 v136, v102, v103
	v_cvt_pk_bf16_f32 v137, v104, v105
	v_add_u32_e32 v255, 0x20800, v245
	global_store_dwordx4 v255, v[134:137], s[98:99] offset:256
	v_fmac_f32_e32 v247, v106, v106
	v_fmac_f32_e32 v247, v107, v107
	v_fmac_f32_e32 v247, v108, v108
	v_fmac_f32_e32 v247, v109, v109
	v_fmac_f32_e32 v254, v102, v102
	v_fmac_f32_e32 v254, v103, v103
	v_fmac_f32_e32 v254, v104, v104
	v_fmac_f32_e32 v254, v105, v105
	v_add_f32_e32 v118, v247, v254
	s_waitcnt vmcnt(15)
	v_lshlrev_b32_e32 v248, 16, v138
	v_and_b32_e32 v249, 0xffff0000, v138
	v_lshlrev_b32_e32 v250, 16, v139
	v_and_b32_e32 v251, 0xffff0000, v139
	v_pk_fma_f32 v[94:95], v[218:219], v[248:249], v[94:95] op_sel_hi:[0,1,1]
	v_pk_fma_f32 v[96:97], v[218:219], v[250:251], v[96:97] op_sel_hi:[0,1,1]
	v_lshlrev_b32_e32 v248, 16, v140
	v_and_b32_e32 v249, 0xffff0000, v140
	v_lshlrev_b32_e32 v250, 16, v141
	v_and_b32_e32 v251, 0xffff0000, v141
	v_pk_fma_f32 v[90:91], v[218:219], v[248:249], v[90:91] op_sel_hi:[0,1,1]
	v_pk_fma_f32 v[92:93], v[218:219], v[250:251], v[92:93] op_sel_hi:[0,1,1]
	v_cvt_pk_bf16_f32 v138, v94, v95
	v_cvt_pk_bf16_f32 v139, v96, v97
	v_cvt_pk_bf16_f32 v140, v90, v91
	v_cvt_pk_bf16_f32 v141, v92, v93
	v_add_u32_e32 v246, 0x41000, v245
	global_store_dwordx4 v246, v[138:141], s[98:99]
	v_mul_f32_e32 v247, v94, v94
	v_fmac_f32_e32 v247, v95, v95
	v_fmac_f32_e32 v247, v96, v96
	v_fmac_f32_e32 v247, v97, v97
	v_mul_f32_e32 v254, v90, v90
	v_fmac_f32_e32 v254, v91, v91
	v_fmac_f32_e32 v254, v92, v92
	v_fmac_f32_e32 v254, v93, v93
	s_waitcnt vmcnt(15)
	v_lshlrev_b32_e32 v248, 16, v150
	v_and_b32_e32 v249, 0xffff0000, v150
	v_lshlrev_b32_e32 v250, 16, v151
	v_and_b32_e32 v251, 0xffff0000, v151
	v_pk_fma_f32 v[86:87], v[218:219], v[248:249], v[86:87] op_sel_hi:[0,1,1]
	v_pk_fma_f32 v[88:89], v[218:219], v[250:251], v[88:89] op_sel_hi:[0,1,1]
	v_lshlrev_b32_e32 v248, 16, v152
	v_and_b32_e32 v249, 0xffff0000, v152
	v_lshlrev_b32_e32 v250, 16, v153
	v_and_b32_e32 v251, 0xffff0000, v153
	v_pk_fma_f32 v[82:83], v[218:219], v[248:249], v[82:83] op_sel_hi:[0,1,1]
	v_pk_fma_f32 v[84:85], v[218:219], v[250:251], v[84:85] op_sel_hi:[0,1,1]
	v_cvt_pk_bf16_f32 v150, v86, v87
	v_cvt_pk_bf16_f32 v151, v88, v89
	v_cvt_pk_bf16_f32 v152, v82, v83
	v_cvt_pk_bf16_f32 v153, v84, v85
	v_add_u32_e32 v255, 0x41000, v245
	global_store_dwordx4 v255, v[150:153], s[98:99] offset:256
	v_fmac_f32_e32 v247, v86, v86
	v_fmac_f32_e32 v247, v87, v87
	v_fmac_f32_e32 v247, v88, v88
	v_fmac_f32_e32 v247, v89, v89
	v_fmac_f32_e32 v254, v82, v82
	v_fmac_f32_e32 v254, v83, v83
	v_fmac_f32_e32 v254, v84, v84
	v_fmac_f32_e32 v254, v85, v85
	v_add_f32_e32 v94, v247, v254
	s_waitcnt vmcnt(15)
	v_lshlrev_b32_e32 v248, 16, v154
	v_and_b32_e32 v249, 0xffff0000, v154
	v_lshlrev_b32_e32 v250, 16, v155
	v_and_b32_e32 v251, 0xffff0000, v155
	v_pk_fma_f32 v[78:79], v[220:221], v[248:249], v[78:79] op_sel_hi:[0,1,1]
	v_pk_fma_f32 v[80:81], v[220:221], v[250:251], v[80:81] op_sel_hi:[0,1,1]
	v_lshlrev_b32_e32 v248, 16, v156
	v_and_b32_e32 v249, 0xffff0000, v156
	v_lshlrev_b32_e32 v250, 16, v157
	v_and_b32_e32 v251, 0xffff0000, v157
	v_pk_fma_f32 v[74:75], v[220:221], v[248:249], v[74:75] op_sel_hi:[0,1,1]
	v_pk_fma_f32 v[76:77], v[220:221], v[250:251], v[76:77] op_sel_hi:[0,1,1]
	v_cvt_pk_bf16_f32 v154, v78, v79
	v_cvt_pk_bf16_f32 v155, v80, v81
	v_cvt_pk_bf16_f32 v156, v74, v75
	v_cvt_pk_bf16_f32 v157, v76, v77
	v_add_u32_e32 v246, 0x61800, v245
	global_store_dwordx4 v246, v[154:157], s[98:99]
	v_mul_f32_e32 v247, v78, v78
	v_fmac_f32_e32 v247, v79, v79
	v_fmac_f32_e32 v247, v80, v80
	v_fmac_f32_e32 v247, v81, v81
	v_mul_f32_e32 v254, v74, v74
	v_fmac_f32_e32 v254, v75, v75
	v_fmac_f32_e32 v254, v76, v76
	v_fmac_f32_e32 v254, v77, v77
	s_waitcnt vmcnt(15)
	v_lshlrev_b32_e32 v248, 16, v162
	v_and_b32_e32 v249, 0xffff0000, v162
	v_lshlrev_b32_e32 v250, 16, v163
	v_and_b32_e32 v251, 0xffff0000, v163
	v_pk_fma_f32 v[70:71], v[220:221], v[248:249], v[70:71] op_sel_hi:[0,1,1]
	v_pk_fma_f32 v[72:73], v[220:221], v[250:251], v[72:73] op_sel_hi:[0,1,1]
	v_lshlrev_b32_e32 v248, 16, v164
	v_and_b32_e32 v249, 0xffff0000, v164
	v_lshlrev_b32_e32 v250, 16, v165
	v_and_b32_e32 v251, 0xffff0000, v165
	v_pk_fma_f32 v[66:67], v[220:221], v[248:249], v[66:67] op_sel_hi:[0,1,1]
	v_pk_fma_f32 v[68:69], v[220:221], v[250:251], v[68:69] op_sel_hi:[0,1,1]
	v_cvt_pk_bf16_f32 v162, v70, v71
	v_cvt_pk_bf16_f32 v163, v72, v73
	v_cvt_pk_bf16_f32 v164, v66, v67
	v_cvt_pk_bf16_f32 v165, v68, v69
	v_add_u32_e32 v255, 0x61800, v245
	global_store_dwordx4 v255, v[162:165], s[98:99] offset:256
	v_fmac_f32_e32 v247, v70, v70
	v_fmac_f32_e32 v247, v71, v71
	v_fmac_f32_e32 v247, v72, v72
	v_fmac_f32_e32 v247, v73, v73
	v_fmac_f32_e32 v254, v66, v66
	v_fmac_f32_e32 v254, v67, v67
	v_fmac_f32_e32 v254, v68, v68
	v_fmac_f32_e32 v254, v69, v69
	v_add_f32_e32 v78, v247, v254
	s_waitcnt vmcnt(15)
; __device__ __forceinline__ unsigned cvt_pk_bf16(float lo, float hi) { unsigned r; asm volatile("v_cvt_pk_bf16_f32 %0, %1, %2" : "=v"(r) : "v"(lo), "v"(hi)); return r; }
; __device__ __forceinline__ float bf_lo(unsigned w) { return __uint_as_float(w << 16); }
; __device__ __forceinline__ float bf_hi(unsigned w) { return __uint_as_float(w & 0xffff0000u); }
;     __device__ __forceinline__ void operator()(EPI_ARGS) const {
;     ...
;                 for (int bj = 0; bj < 2; ++bj) { const size_t off = (size_t)(row0 + ai * HALF + m * 16) * ldc + col0 + bj * HALF;
;                     if (RES_BF16) { const u32x4 rw = *(const u32x4*)((const bf16*)resid + off); r0[m][bj] = __builtin_bit_cast(f32x4, rw); }
;                     else { r0[m][bj] = *(const f32x4*)((const float*)resid + off); r1[m][bj] = *(const f32x4*)((const float*)resid + off + 4); } }
; #pragma unroll
;             for (int m = 0; m < 4; ++m) { const int row = row0 + ai * HALF + m * 16; const size_t off = (size_t)row * ldc + col0; float ss = 0.f, mx = 0.f;
; #pragma unroll
;                 for (int bj = 0; bj < 2; ++bj) {
;                     f32x4 a0, a1;
;                     if (RES_BF16) { const u32x4 rw = __builtin_bit_cast(u32x4, r0[m][bj]); a0 = (f32x4){bf_lo(rw.x), bf_hi(rw.x), bf_lo(rw.y), bf_hi(rw.y)}; a1 = (f32x4){bf_lo(rw.z), bf_hi(rw.z), bf_lo(rw.w), bf_hi(rw.w)};
;                         if (RES_SCALE) { const float rf = rfac[row]; a0 = a0 * rf; a1 = a1 * rf; } }
;                     else { a0 = r0[m][bj]; a1 = r1[m][bj]; }
;                     const f32x4 v0 = acc[ai][bj][m][0] + a0, v1 = acc[ai][bj][m][1] + a1;
;                     u32x4 w; w.x = cvt_pk_bf16(v0[0], v0[1]); w.y = cvt_pk_bf16(v0[2], v0[3]); w.z = cvt_pk_bf16(v1[0], v1[1]); w.w = cvt_pk_bf16(v1[2], v1[3]); *(u32x4*)(ob + off + bj * HALF) = w;
;                     ss += (v0[0] * v0[0] + v0[1] * v0[1]) + (v0[2] * v0[2] + v0[3] * v0[3]) + (v1[0] * v1[0] + v1[1] * v1[1]) + (v1[2] * v1[2] + v1[3] * v1[3]);
;                     if (rowmax) mx = fmaxf(mx, fmaxf(fmaxf(fmaxf(fabsf(v0[0]), fabsf(v0[1])), fmaxf(fabsf(v0[2]), fabsf(v0[3]))), fmaxf(fmaxf(fabsf(v1[0]), fabsf(v1[1])), fmaxf(fabsf(v1[2]), fabsf(v1[3]))))); }
	v_lshlrev_b32_e32 v248, 16, v166
	v_and_b32_e32 v249, 0xffff0000, v166
	v_lshlrev_b32_e32 v250, 16, v167
	v_and_b32_e32 v251, 0xffff0000, v167
	v_pk_fma_f32 v[62:63], v[222:223], v[248:249], v[62:63] op_sel_hi:[0,1,1]
	v_pk_fma_f32 v[64:65], v[222:223], v[250:251], v[64:65] op_sel_hi:[0,1,1]
	v_lshlrev_b32_e32 v248, 16, v168
	v_and_b32_e32 v249, 0xffff0000, v168
	v_lshlrev_b32_e32 v250, 16, v169
	v_and_b32_e32 v251, 0xffff0000, v169
	v_pk_fma_f32 v[58:59], v[222:223], v[248:249], v[58:59] op_sel_hi:[0,1,1]
	v_pk_fma_f32 v[60:61], v[222:223], v[250:251], v[60:61] op_sel_hi:[0,1,1]
	v_cvt_pk_bf16_f32 v166, v62, v63
	v_cvt_pk_bf16_f32 v167, v64, v65
	v_cvt_pk_bf16_f32 v168, v58, v59
	v_cvt_pk_bf16_f32 v169, v60, v61
	v_add_u32_e32 v246, 0x104000, v245
	global_store_dwordx4 v246, v[166:169], s[98:99]
	v_mul_f32_e32 v247, v62, v62
	v_fmac_f32_e32 v247, v63, v63
	v_fmac_f32_e32 v247, v64, v64
	v_fmac_f32_e32 v247, v65, v65
	v_mul_f32_e32 v254, v58, v58
	v_fmac_f32_e32 v254, v59, v59
	v_fmac_f32_e32 v254, v60, v60
	v_fmac_f32_e32 v254, v61, v61
	s_waitcnt vmcnt(15)
	v_lshlrev_b32_e32 v248, 16, v170
	v_and_b32_e32 v249, 0xffff0000, v170
	v_lshlrev_b32_e32 v250, 16, v171
	v_and_b32_e32 v251, 0xffff0000, v171
	v_pk_fma_f32 v[54:55], v[222:223], v[248:249], v[54:55] op_sel_hi:[0,1,1]
	v_pk_fma_f32 v[56:57], v[222:223], v[250:251], v[56:57] op_sel_hi:[0,1,1]
	v_lshlrev_b32_e32 v248, 16, v172
	v_and_b32_e32 v249, 0xffff0000, v172
	v_lshlrev_b32_e32 v250, 16, v173
	v_and_b32_e32 v251, 0xffff0000, v173
	v_pk_fma_f32 v[50:51], v[222:223], v[248:249], v[50:51] op_sel_hi:[0,1,1]
	v_pk_fma_f32 v[52:53], v[222:223], v[250:251], v[52:53] op_sel_hi:[0,1,1]
	v_cvt_pk_bf16_f32 v170, v54, v55
	v_cvt_pk_bf16_f32 v171, v56, v57
	v_cvt_pk_bf16_f32 v172, v50, v51
	v_cvt_pk_bf16_f32 v173, v52, v53
	v_add_u32_e32 v255, 0x104000, v245
	global_store_dwordx4 v255, v[170:173], s[98:99] offset:256
	v_fmac_f32_e32 v247, v54, v54
	v_fmac_f32_e32 v247, v55, v55
	v_fmac_f32_e32 v247, v56, v56
	v_fmac_f32_e32 v247, v57, v57
	v_fmac_f32_e32 v254, v50, v50
	v_fmac_f32_e32 v254, v51, v51
	v_fmac_f32_e32 v254, v52, v52
	v_fmac_f32_e32 v254, v53, v53
	v_add_f32_e32 v62, v247, v254
	s_waitcnt vmcnt(15)
	v_lshlrev_b32_e32 v248, 16, v174
	v_and_b32_e32 v249, 0xffff0000, v174
	v_lshlrev_b32_e32 v250, 16, v175
	v_and_b32_e32 v251, 0xffff0000, v175
	v_pk_fma_f32 v[46:47], v[224:225], v[248:249], v[46:47] op_sel_hi:[0,1,1]
	v_pk_fma_f32 v[48:49], v[224:225], v[250:251], v[48:49] op_sel_hi:[0,1,1]
	v_lshlrev_b32_e32 v248, 16, v176
	v_and_b32_e32 v249, 0xffff0000, v176
	v_lshlrev_b32_e32 v250, 16, v177
	v_and_b32_e32 v251, 0xffff0000, v177
	v_pk_fma_f32 v[42:43], v[224:225], v[248:249], v[42:43] op_sel_hi:[0,1,1]
	v_pk_fma_f32 v[44:45], v[224:225], v[250:251], v[44:45] op_sel_hi:[0,1,1]
	v_cvt_pk_bf16_f32 v174, v46, v47
	v_cvt_pk_bf16_f32 v175, v48, v49
	v_cvt_pk_bf16_f32 v176, v42, v43
	v_cvt_pk_bf16_f32 v177, v44, v45
	v_add_u32_e32 v246, 0x124800, v245
	global_store_dwordx4 v246, v[174:177], s[98:99]
	v_mul_f32_e32 v247, v46, v46
	v_fmac_f32_e32 v247, v47, v47
	v_fmac_f32_e32 v247, v48, v48
	v_fmac_f32_e32 v247, v49, v49
	v_mul_f32_e32 v254, v42, v42
	v_fmac_f32_e32 v254, v43, v43
	v_fmac_f32_e32 v254, v44, v44
	v_fmac_f32_e32 v254, v45, v45
	s_waitcnt vmcnt(15)
	v_lshlrev_b32_e32 v248, 16, v178
	v_and_b32_e32 v249, 0xffff0000, v178
	v_lshlrev_b32_e32 v250, 16, v179
	v_and_b32_e32 v251, 0xffff0000, v179
	v_pk_fma_f32 v[38:39], v[224:225], v[248:249], v[38:39] op_sel_hi:[0,1,1]
	v_pk_fma_f32 v[40:41], v[224:225], v[250:251], v[40:41] op_sel_hi:[0,1,1]
	v_lshlrev_b32_e32 v248, 16, v180
	v_and_b32_e32 v249, 0xffff0000, v180
	v_lshlrev_b32_e32 v250, 16, v181
	v_and_b32_e32 v251, 0xffff0000, v181
	v_pk_fma_f32 v[34:35], v[224:225], v[248:249], v[34:35] op_sel_hi:[0,1,1]
	v_pk_fma_f32 v[36:37], v[224:225], v[250:251], v[36:37] op_sel_hi:[0,1,1]
	v_cvt_pk_bf16_f32 v178, v38, v39
	v_cvt_pk_bf16_f32 v179, v40, v41
	v_cvt_pk_bf16_f32 v180, v34, v35
	v_cvt_pk_bf16_f32 v181, v36, v37
	v_add_u32_e32 v255, 0x124800, v245
	global_store_dwordx4 v255, v[178:181], s[98:99] offset:256
	v_fmac_f32_e32 v247, v38, v38
	v_fmac_f32_e32 v247, v39, v39
	v_fmac_f32_e32 v247, v40, v40
	v_fmac_f32_e32 v247, v41, v41
	v_fmac_f32_e32 v254, v34, v34
	v_fmac_f32_e32 v254, v35, v35
	v_fmac_f32_e32 v254, v36, v36
	v_fmac_f32_e32 v254, v37, v37
	v_add_f32_e32 v46, v247, v254
	s_waitcnt vmcnt(15)
	v_lshlrev_b32_e32 v248, 16, v198
	v_and_b32_e32 v249, 0xffff0000, v198
	v_lshlrev_b32_e32 v250, 16, v199
	v_and_b32_e32 v251, 0xffff0000, v199
	v_pk_fma_f32 v[30:31], v[226:227], v[248:249], v[30:31] op_sel_hi:[0,1,1]
	v_pk_fma_f32 v[32:33], v[226:227], v[250:251], v[32:33] op_sel_hi:[0,1,1]
	v_lshlrev_b32_e32 v248, 16, v200
	v_and_b32_e32 v249, 0xffff0000, v200
	v_lshlrev_b32_e32 v250, 16, v201
	v_and_b32_e32 v251, 0xffff0000, v201
	v_pk_fma_f32 v[26:27], v[226:227], v[248:249], v[26:27] op_sel_hi:[0,1,1]
	v_pk_fma_f32 v[28:29], v[226:227], v[250:251], v[28:29] op_sel_hi:[0,1,1]
	v_cvt_pk_bf16_f32 v198, v30, v31
	v_cvt_pk_bf16_f32 v199, v32, v33
	v_cvt_pk_bf16_f32 v200, v26, v27
	v_cvt_pk_bf16_f32 v201, v28, v29
	v_add_u32_e32 v246, 0x145000, v245
	global_store_dwordx4 v246, v[198:201], s[98:99]
	v_mul_f32_e32 v247, v30, v30
	v_fmac_f32_e32 v247, v31, v31
	v_fmac_f32_e32 v247, v32, v32
	v_fmac_f32_e32 v247, v33, v33
	v_mul_f32_e32 v254, v26, v26
	v_fmac_f32_e32 v254, v27, v27
	v_fmac_f32_e32 v254, v28, v28
	v_fmac_f32_e32 v254, v29, v29
	s_waitcnt vmcnt(15)
;     __device__ __forceinline__ void operator()(EPI_ARGS) const {
;     ...
;                 for (int bj = 0; bj < 2; ++bj) { const size_t off = (size_t)(row0 + ai * HALF + m * 16) * ldc + col0 + bj * HALF;
;                     if (RES_BF16) { const u32x4 rw = *(const u32x4*)((const bf16*)resid + off); r0[m][bj] = __builtin_bit_cast(f32x4, rw); }
;                     else { r0[m][bj] = *(const f32x4*)((const float*)resid + off); r1[m][bj] = *(const f32x4*)((const float*)resid + off + 4); } }
; #pragma unroll
;             for (int m = 0; m < 4; ++m) { const int row = row0 + ai * HALF + m * 16; const size_t off = (size_t)row * ldc + col0; float ss = 0.f, mx = 0.f;
; #pragma unroll
;                 for (int bj = 0; bj < 2; ++bj) {
;                     f32x4 a0, a1;
;                     if (RES_BF16) { const u32x4 rw = __builtin_bit_cast(u32x4, r0[m][bj]); a0 = (f32x4){bf_lo(rw.x), bf_hi(rw.x), bf_lo(rw.y), bf_hi(rw.y)}; a1 = (f32x4){bf_lo(rw.z), bf_hi(rw.z), bf_lo(rw.w), bf_hi(rw.w)};
;                         if (RES_SCALE) { const float rf = rfac[row]; a0 = a0 * rf; a1 = a1 * rf; } }
;                     else { a0 = r0[m][bj]; a1 = r1[m][bj]; }
;                     const f32x4 v0 = acc[ai][bj][m][0] + a0, v1 = acc[ai][bj][m][1] + a1;
;                     u32x4 w; w.x = cvt_pk_bf16(v0[0], v0[1]); w.y = cvt_pk_bf16(v0[2], v0[3]); w.z = cvt_pk_bf16(v1[0], v1[1]); w.w = cvt_pk_bf16(v1[2], v1[3]); *(u32x4*)(ob + off + bj * HALF) = w;
;                     ss += (v0[0] * v0[0] + v0[1] * v0[1]) + (v0[2] * v0[2] + v0[3] * v0[3]) + (v1[0] * v1[0] + v1[1] * v1[1]) + (v1[2] * v1[2] + v1[3] * v1[3]);
;                     if (rowmax) mx = fmaxf(mx, fmaxf(fmaxf(fmaxf(fabsf(v0[0]), fabsf(v0[1])), fmaxf(fabsf(v0[2]), fabsf(v0[3]))), fmaxf(fmaxf(fabsf(v1[0]), fabsf(v1[1])), fmaxf(fabsf(v1[2]), fabsf(v1[3]))))); }
;                 ss += __shfl_xor(ss, 16); ss += __shfl_xor(ss, 32); ssv[ai * 4 + m] = ss;
;                 if (rowmax) { mx = fmaxf(mx, __shfl_xor(mx, 16)); mx = fmaxf(mx, __shfl_xor(mx, 32)); } mxv[ai * 4 + m] = mx; }
;             asm volatile("" ::: "memory"); }
;         float s0 = 0.f, s1 = 0.f, m0 = 0.f, m1 = 0.f;
; #pragma unroll
;         for (int k = 0; k < 8; ++k) if ((k >> 1) == fq) { if (k & 1) { s1 = ssv[k]; m1 = mxv[k]; } else { s0 = ssv[k]; m0 = mxv[k]; } }
;         const int rq = row0 + (fq >> 1) * HALF + (fq & 1) * 32;
	v_lshlrev_b32_e32 v248, 16, v202
	v_and_b32_e32 v249, 0xffff0000, v202
	v_lshlrev_b32_e32 v250, 16, v203
	v_and_b32_e32 v251, 0xffff0000, v203
	v_pk_fma_f32 v[22:23], v[226:227], v[248:249], v[22:23] op_sel_hi:[0,1,1]
	v_pk_fma_f32 v[24:25], v[226:227], v[250:251], v[24:25] op_sel_hi:[0,1,1]
	v_lshlrev_b32_e32 v248, 16, v204
	v_and_b32_e32 v249, 0xffff0000, v204
	v_lshlrev_b32_e32 v250, 16, v205
	v_and_b32_e32 v251, 0xffff0000, v205
	v_pk_fma_f32 v[18:19], v[226:227], v[248:249], v[18:19] op_sel_hi:[0,1,1]
	v_pk_fma_f32 v[20:21], v[226:227], v[250:251], v[20:21] op_sel_hi:[0,1,1]
	v_cvt_pk_bf16_f32 v202, v22, v23
	v_cvt_pk_bf16_f32 v203, v24, v25
	v_cvt_pk_bf16_f32 v204, v18, v19
	v_cvt_pk_bf16_f32 v205, v20, v21
	v_add_u32_e32 v255, 0x145000, v245
	global_store_dwordx4 v255, v[202:205], s[98:99] offset:256
	v_fmac_f32_e32 v247, v22, v22
	v_fmac_f32_e32 v247, v23, v23
	v_fmac_f32_e32 v247, v24, v24
	v_fmac_f32_e32 v247, v25, v25
	v_fmac_f32_e32 v254, v18, v18
	v_fmac_f32_e32 v254, v19, v19
	v_fmac_f32_e32 v254, v20, v20
	v_fmac_f32_e32 v254, v21, v21
	v_add_f32_e32 v30, v247, v254
	s_waitcnt vmcnt(15)
	v_lshlrev_b32_e32 v248, 16, v206
	v_and_b32_e32 v249, 0xffff0000, v206
	v_lshlrev_b32_e32 v250, 16, v207
	v_and_b32_e32 v251, 0xffff0000, v207
	v_pk_fma_f32 v[14:15], v[228:229], v[248:249], v[14:15] op_sel_hi:[0,1,1]
	v_pk_fma_f32 v[16:17], v[228:229], v[250:251], v[16:17] op_sel_hi:[0,1,1]
	v_lshlrev_b32_e32 v248, 16, v208
	v_and_b32_e32 v249, 0xffff0000, v208
	v_lshlrev_b32_e32 v250, 16, v209
	v_and_b32_e32 v251, 0xffff0000, v209
	v_pk_fma_f32 v[10:11], v[228:229], v[248:249], v[10:11] op_sel_hi:[0,1,1]
	v_pk_fma_f32 v[12:13], v[228:229], v[250:251], v[12:13] op_sel_hi:[0,1,1]
	v_cvt_pk_bf16_f32 v206, v14, v15
	v_cvt_pk_bf16_f32 v207, v16, v17
	v_cvt_pk_bf16_f32 v208, v10, v11
	v_cvt_pk_bf16_f32 v209, v12, v13
	v_add_u32_e32 v246, 0x165800, v245
	global_store_dwordx4 v246, v[206:209], s[98:99]
	v_mul_f32_e32 v247, v14, v14
	v_fmac_f32_e32 v247, v15, v15
	v_fmac_f32_e32 v247, v16, v16
	v_fmac_f32_e32 v247, v17, v17
	v_mul_f32_e32 v254, v10, v10
	v_fmac_f32_e32 v254, v11, v11
	v_fmac_f32_e32 v254, v12, v12
	v_fmac_f32_e32 v254, v13, v13
	s_waitcnt vmcnt(15)
	v_lshlrev_b32_e32 v248, 16, v210
	v_and_b32_e32 v249, 0xffff0000, v210
	v_lshlrev_b32_e32 v250, 16, v211
	v_and_b32_e32 v251, 0xffff0000, v211
	v_pk_fma_f32 v[6:7], v[228:229], v[248:249], v[6:7] op_sel_hi:[0,1,1]
	v_pk_fma_f32 v[8:9], v[228:229], v[250:251], v[8:9] op_sel_hi:[0,1,1]
	v_lshlrev_b32_e32 v248, 16, v212
	v_and_b32_e32 v249, 0xffff0000, v212
	v_lshlrev_b32_e32 v250, 16, v213
	v_and_b32_e32 v251, 0xffff0000, v213
	v_pk_fma_f32 v[2:3], v[228:229], v[248:249], v[2:3] op_sel_hi:[0,1,1]
	v_pk_fma_f32 v[4:5], v[228:229], v[250:251], v[4:5] op_sel_hi:[0,1,1]
	v_cvt_pk_bf16_f32 v210, v6, v7
	v_cvt_pk_bf16_f32 v211, v8, v9
	v_cvt_pk_bf16_f32 v212, v2, v3
	v_cvt_pk_bf16_f32 v213, v4, v5
	v_add_u32_e32 v255, 0x165800, v245
	global_store_dwordx4 v255, v[210:213], s[98:99] offset:256
	v_fmac_f32_e32 v247, v6, v6
	v_fmac_f32_e32 v247, v7, v7
	v_fmac_f32_e32 v247, v8, v8
	v_fmac_f32_e32 v247, v9, v9
	v_fmac_f32_e32 v254, v2, v2
	v_fmac_f32_e32 v254, v3, v3
	v_fmac_f32_e32 v254, v4, v4
	v_fmac_f32_e32 v254, v5, v5
	v_add_f32_e32 v14, v247, v254
	v_and_b32_e32 v255, 63, v0
	v_xor_b32_e32 v252, 16, v255
	v_xor_b32_e32 v253, 32, v255
	v_lshlrev_b32_e32 v252, 2, v252
	v_lshlrev_b32_e32 v253, 2, v253
	ds_bpermute_b32 v147, v252, v146
	ds_bpermute_b32 v119, v252, v118
	ds_bpermute_b32 v95, v252, v94
	ds_bpermute_b32 v79, v252, v78
	ds_bpermute_b32 v63, v252, v62
	ds_bpermute_b32 v47, v252, v46
	ds_bpermute_b32 v31, v252, v30
	ds_bpermute_b32 v15, v252, v14
	s_waitcnt lgkmcnt(0)
	v_add_f32_e32 v146, v146, v147
	v_add_f32_e32 v118, v118, v119
	v_add_f32_e32 v94, v94, v95
	v_add_f32_e32 v78, v78, v79
	v_add_f32_e32 v62, v62, v63
	v_add_f32_e32 v46, v46, v47
	v_add_f32_e32 v30, v30, v31
	v_add_f32_e32 v14, v14, v15
	ds_bpermute_b32 v147, v253, v146
	ds_bpermute_b32 v119, v253, v118
	ds_bpermute_b32 v95, v253, v94
	ds_bpermute_b32 v79, v253, v78
	ds_bpermute_b32 v63, v253, v62
	ds_bpermute_b32 v47, v253, v46
	ds_bpermute_b32 v31, v253, v30
	ds_bpermute_b32 v15, v253, v14
	s_waitcnt lgkmcnt(0)
	v_add_f32_e32 v146, v146, v147
	v_add_f32_e32 v118, v118, v119
	v_add_f32_e32 v94, v94, v95
	v_add_f32_e32 v78, v78, v79
	v_add_f32_e32 v62, v62, v63
	v_add_f32_e32 v46, v46, v47
	v_add_f32_e32 v30, v30, v31
	v_add_f32_e32 v14, v14, v15
	v_cndmask_b32_e64 v248, 0, v146, s[2:3]
	v_cndmask_b32_e64 v249, 0, v118, s[2:3]
	v_cndmask_b32_e64 v248, v248, v94, s[4:5]
	v_cndmask_b32_e64 v249, v249, v78, s[4:5]
	v_cndmask_b32_e64 v248, v248, v62, s[6:7]
	v_cndmask_b32_e64 v249, v249, v46, s[6:7]
	v_cndmask_b32_e64 v248, v248, v30, s[8:9]
	v_cndmask_b32_e64 v249, v249, v14, s[8:9]
	v_lshl_add_u32 v250, s78, 8, v189
	v_add_u32_e32 v250, v188, v250
	v_lshlrev_b32_e32 v250, 2, v250
	global_atomic_add_f32 v250, v248, s[62:63]
	global_atomic_add_f32 v250, v249, s[62:63] offset:64
	s_andn2_b64 vcc, exec, s[10:11]
	s_mov_b64 s[14:15], -1
	s_cbranch_vccnz .LBB0_781
	s_andn2_b64 vcc, exec, s[0:1]
	s_cbranch_vccnz .LBB0_780
	s_barrier
	s_branch .LBB0_780

; __device__ __forceinline__ const char* unitA(const Gemm& g, const Unit& u) { return (const char*)(g.A + (size_t)(u.z / g.zdiv) * g.sAhi + (size_t)(u.z % g.zdiv) * g.sAlo + (size_t)u.pm * BM * g.lda); }
; __device__ __forceinline__ const char* unitB(const Gemm& g, const Unit& u) { return (const char*)(g.Bt + (size_t)(u.z / g.zdiv) * g.sBhi + (size_t)(u.z % g.zdiv) * g.sBlo + (size_t)(u.pm / g.bdiv) * g.sBpm + (size_t)u.pn * BM * g.ldb); }
; #define PG8_STAGE(bufoff, gbase, voff) do { if constexpr (VAR != 1 && VAR != 3) { _Pragma("unroll") for (int _i = 0; _i < 2; ++_i) \
;         asm volatile("s_mov_b32 m0, %2\n\ts_nop 0\n\tglobal_load_lds_dwordx4 %0, %1" :: "v"((voff)[_i]), "s"((const char*)(gbase)), "s"(ldsbase + (unsigned)((bufoff) + _i * 8192)) : "memory", "m0"); } } while (0)
; #define PG8_WAIT_V(n) asm volatile("s_waitcnt vmcnt(" #n ")" ::: "memory")
; #define PG8_BAR do { if constexpr (VAR != 3) __builtin_amdgcn_s_barrier(); } while (0)
;     ...
;     for (int i = 0; i < 2; ++i) { int R, C; stage_rc(tid * 16 + i * 8192, R, C); const int Rb = Epi::PERM ? ((R & ~31) + perm32(R & 31)) : R;
;         voffA[i] = (unsigned)(R * g.lda + C) * 2u; voffB[i] = (unsigned)(Rb * g.ldb + C) * 2u; }
;     const size_t kstep = (size_t)(BK * 2);
;     const size_t hstepA = (size_t)HALF * g.lda * 2, hstepB = (size_t)HALF * g.ldb * 2;
;     const unsigned ldsw = (unsigned)wid * 1024u;
;     const unsigned ldsbase = (unsigned)__builtin_amdgcn_readfirstlane((int)((unsigned)(size_t)lds + ldsw)); (void)ldsw;
;     const int aoff = lds_byte(wr * 64 + fr, fq * 8), boff = lds_byte(wc * 32 + fr, fq * 8);
;     ...
;     const char* cA = unitA(g, cur); const char* cB = unitB(g, cur);
;     PG8_STAGE(PG8_SB(0, 0), cB, voffB); PG8_STAGE(PG8_SB(0, 1), cB + hstepB, voffB); PG8_STAGE(PG8_SA(0, 0), cA, voffA); PG8_STAGE(PG8_SA(0, 1), cA + hstepA, voffA);
;     if (wr == 1) PG8_BAR;
;     PG8_WAIT_V(2); PG8_BAR;
;     PG8_STAGE(PG8_SB(1, 0), cB + kstep, voffB); PG8_STAGE(PG8_SA(1, 0), cA + kstep, voffA); PG8_STAGE(PG8_SB(1, 1), cB + hstepB + kstep, voffB);
.LBB0_878:
	v_lshlrev_b32_e32 v1, 4, v0
	s_waitcnt vmcnt(47)
	v_and_b32_e32 v2, 32, v0
	v_bitop3_b32 v1, v1, v2, 48 bitop3:0x6c
	v_and_or_b32 v2, v0, 64, v1
	v_lshrrev_b32_e32 v1, 1, v0
	v_lshrrev_b32_e32 v4, 5, v0
	v_and_b32_e32 v1, 24, v1
	v_and_b32_e32 v4, 4, v4
	v_bfe_u32 v5, v0, 2, 2
	v_bfe_u32 v3, v0, 2, 4
	v_or3_b32 v4, v4, v5, v1
	v_lshrrev_b32_e32 v1, 3, v0
	v_and_or_b32 v5, v1, 48, v3
	s_waitcnt vmcnt(46)
	v_and_or_b32 v6, v1, 32, v4
	v_mul_u32_u24_e32 v1, 0x2080, v5
	v_add_u32_e32 v1, v1, v2
	v_bfe_u32 v5, v0, 3, 25
	v_or_b32_e32 v5, 64, v5
	s_movk_i32 s1, 0x70
	v_and_or_b32 v3, v5, s1, v3
	s_movk_i32 s1, 0x60
	v_and_or_b32 v4, v5, s1, v4
	s_lshl_b32 s1, s5, 10
	s_add_i32 s15, s1, 0
	s_ashr_i32 s1, s0, 31
	s_lshr_b32 s2, s1, 28
	s_add_i32 s2, s0, s2
	s_ashr_i32 s2, s2, 4
	s_ashr_i32 s3, s2, 31
	s_lshr_b32 s6, s4, 8
	s_lshl_b64 s[2:3], s[2:3], 23
	s_add_u32 s7, s21, s2
	v_readlane_b32 s2, v244, 51
	s_addc_u32 s8, s2, s3
	s_ashr_i32 s67, s66, 31
	s_lshl_b64 s[2:3], s[66:67], 21
	s_add_u32 s68, s7, s2
	v_lshl_or_b32 v172, v6, 13, v2
	s_addc_u32 s69, s8, s3
	s_add_i32 s17, s15, 0x10000
	s_mov_b32 m0, s17
	s_nop 0
	global_load_lds_dwordx4 v172, s[68:69]
	s_add_i32 s19, s15, 0x12000
	v_lshl_or_b32 v174, v4, 13, v2
	s_mov_b32 m0, s19
	s_nop 0
	global_load_lds_dwordx4 v174, s[68:69]
	s_add_u32 s2, s68, 0x100000
	s_addc_u32 s3, s69, 0
	s_add_i32 s23, s15, 0x14000
	s_mov_b32 m0, s23
	s_nop 0
	global_load_lds_dwordx4 v172, s[2:3]
	s_add_i32 s26, s15, 0x16000
	s_mov_b32 m0, s26
	s_nop 0
	global_load_lds_dwordx4 v174, s[2:3]
	s_mul_i32 s2, s0, 0x208000
	s_mov_b32 s3, 0
	s_add_u32 s70, s98, s2
	s_addc_u32 s71, s99, s3
	s_mov_b32 m0, s15
	s_nop 0
	global_load_lds_dwordx4 v1, s[70:71]
	s_add_i32 s27, s15, 0x2000
	v_mul_u32_u24_e32 v173, 0x2080, v3
	v_add_u32_e32 v173, v173, v2
	s_mov_b32 m0, s27
	s_nop 0
	global_load_lds_dwordx4 v173, s[70:71]
	s_add_u32 s2, s70, 0x104000
	s_addc_u32 s3, s71, 0
	s_add_i32 s28, s15, 0x4000
	s_mov_b32 m0, s28
	s_nop 0
	global_load_lds_dwordx4 v1, s[2:3]
	s_add_i32 s29, s15, 0x6000
	s_mov_b32 m0, s29
	s_nop 0
	global_load_lds_dwordx4 v173, s[2:3]
	s_cmp_eq_u32 s6, 1
	s_mov_b32 s14, 0
	s_cselect_b64 s[8:9], -1, 0
	s_cmp_lg_u32 s6, 1
	s_cbranch_scc1 .LBB0_880
	s_barrier

; __device__ __forceinline__ const char* unitA(const Gemm& g, const Unit& u) { return (const char*)(g.A + (size_t)(u.z / g.zdiv) * g.sAhi + (size_t)(u.z % g.zdiv) * g.sAlo + (size_t)u.pm * BM * g.lda); }
; __device__ __forceinline__ const char* unitB(const Gemm& g, const Unit& u) { return (const char*)(g.Bt + (size_t)(u.z / g.zdiv) * g.sBhi + (size_t)(u.z % g.zdiv) * g.sBlo + (size_t)(u.pm / g.bdiv) * g.sBpm + (size_t)u.pn * BM * g.ldb); }
; #define PG8_STAGE(bufoff, gbase, voff) do { if constexpr (VAR != 1 && VAR != 3) { _Pragma("unroll") for (int _i = 0; _i < 2; ++_i) \
;         asm volatile("s_mov_b32 m0, %2\n\ts_nop 0\n\tglobal_load_lds_dwordx4 %0, %1" :: "v"((voff)[_i]), "s"((const char*)(gbase)), "s"(ldsbase + (unsigned)((bufoff) + _i * 8192)) : "memory", "m0"); } } while (0)
; #define PG8_LDA(dst, b, h) do { if constexpr (VAR < 2) _Pragma("unroll") for (int m = 0; m < 4; ++m) _Pragma("unroll") for (int k = 0; k < 2; ++k) dst[m][k] = *(const LAS bf16x8*)(lds + PG8_SA(b, h) + aoff + m * 2048 + k * 1024); } while (0)
; #define PG8_LDB(dst, b, h) do { if constexpr (VAR < 2) _Pragma("unroll") for (int n = 0; n < 2; ++n) _Pragma("unroll") for (int k = 0; k < 2; ++k) dst[n][k] = *(const LAS bf16x8*)(lds + PG8_SB(b, h) + boff + n * 2048 + k * 1024); } while (0)
; #define PG8_SCHED __builtin_amdgcn_sched_barrier(0)
;     ...
;     for (;;) {
;         const bool has_next = S.next(ui + 1, nxt);
;         const char* nA = has_next ? unitA(g, nxt) : cA; const char* nB = has_next ? unitB(g, nxt) : cB;
;         for (int t = 0; t < nt; t += 2) {
;             const bool last = (t == nt - 2);
;             const char* a1 = cA + (size_t)(t + 1) * kstep;
;             const char* a2 = last ? nA : cA + (size_t)(t + 2) * kstep; const char* b2 = last ? nB : cB + (size_t)(t + 2) * kstep;
;             const char* a3 = a2 + kstep; const char* b3 = b2 + kstep;
;             PG8_LDB(B0, 0, 0); PG8_LDB(B1, 0, 1); PG8_SCHED; PG8_LDA(At, 0, 0); PG8_STAGE(PG8_SA(1, 1), a1 + hstepA, voffA);
;             PG8_WAIT_V(8); PG8_WAIT_L(0); PG8_BAR; PG8_MMA(0, 0, At, B0); PG8_MMA(0, 1, At, B1); PG8_BAR; PG8_SCHED;
;             PG8_LDA(At, 0, 1); PG8_STAGE(PG8_SB(0, 0), b2, voffB); PG8_STAGE(PG8_SB(0, 1), b2 + hstepB, voffB); PG8_STAGE(PG8_SA(0, 0), a2, voffA);
;             PG8_WAIT_V(8); PG8_WAIT_L(0); PG8_BAR; PG8_MMA(1, 0, At, B0); PG8_MMA(1, 1, At, B1); PG8_BAR; PG8_SCHED;
.LBB0_891:
	s_ashr_i32 s59, s58, 31
	s_mul_i32 s24, s58, 0x208000
	s_mov_b32 s25, 0
	s_add_u32 s64, s98, s24
	s_addc_u32 s65, s99, s25
	s_and_b64 s[6:7], s[6:7], exec
	s_cselect_b32 s1, s65, s71
	s_cselect_b32 s24, s64, s70
	s_add_u32 s25, s70, 0x100
	s_addc_u32 s39, s71, 0
	s_add_u32 s59, s68, 0x100
	s_addc_u32 s84, s69, 0
	s_add_u32 s6, s70, 0x104080
	s_addc_u32 s7, s71, 0
	s_mov_b32 s85, -2
	s_waitcnt vmcnt(41)
	s_waitcnt vmcnt(40)
	s_waitcnt vmcnt(38)
	s_waitcnt vmcnt(35)
	s_waitcnt vmcnt(34)
	s_waitcnt vmcnt(32)
	ds_read_b128 v[134:137], v201
	ds_read_b128 v[138:141], v201 offset:1024
	ds_read_b128 v[142:145], v201 offset:2048
	ds_read_b128 v[146:149], v201 offset:3072
	ds_read_b128 v[150:153], v202
	ds_read_b128 v[154:157], v202 offset:1024
	ds_read_b128 v[158:161], v202 offset:2048
	ds_read_b128 v[162:165], v202 offset:3072
	s_cmp_eq_u32 s85, 60
	s_cselect_b32 s72, s24, s25
	s_cselect_b32 s73, s1, s39
	s_cselect_b32 s70, s60, s59
	s_cselect_b32 s71, s61, s84
	s_add_u32 s68, s72, 0x80
	s_addc_u32 s69, s73, 0
	ds_read_b128 v[166:169], v203
	ds_read_b128 v[210:213], v203 offset:1024
	ds_read_b128 v[214:217], v203 offset:2048
	ds_read_b128 v[218:221], v203 offset:3072
	ds_read_b128 v[222:225], v203 offset:4096
	ds_read_b128 v[226:229], v203 offset:5120
	ds_read_b128 v[230:233], v203 offset:6144
	ds_read_b128 v[234:237], v203 offset:7168
	s_mov_b32 m0, s77
	s_nop 0
	global_load_lds_dwordx4 v1, s[6:7]
	s_mov_b32 m0, s79
	s_nop 0
	global_load_lds_dwordx4 v173, s[6:7]
	s_waitcnt vmcnt(8) lgkmcnt(0)
	s_barrier
	v_mfma_f32_16x16x32_bf16 v[126:129], v[134:137], v[166:169], 0
	v_mfma_f32_16x16x32_bf16 v[122:125], v[142:145], v[166:169], 0
	v_mfma_f32_16x16x32_bf16 v[110:113], v[134:137], v[214:217], 0
	v_mfma_f32_16x16x32_bf16 v[106:109], v[142:145], v[214:217], 0
	v_mfma_f32_16x16x32_bf16 v[94:97], v[134:137], v[222:225], 0
	v_mfma_f32_16x16x32_bf16 v[90:93], v[142:145], v[222:225], 0
	v_mfma_f32_16x16x32_bf16 v[78:81], v[134:137], v[230:233], 0
	v_mfma_f32_16x16x32_bf16 v[74:77], v[142:145], v[230:233], 0
	v_mfma_f32_16x16x32_bf16 v[126:129], v[138:141], v[210:213], v[126:129]
	v_mfma_f32_16x16x32_bf16 v[122:125], v[146:149], v[210:213], v[122:125]
	v_mfma_f32_16x16x32_bf16 v[110:113], v[138:141], v[218:221], v[110:113]
	v_mfma_f32_16x16x32_bf16 v[106:109], v[146:149], v[218:221], v[106:109]
	v_mfma_f32_16x16x32_bf16 v[94:97], v[138:141], v[226:229], v[94:97]
	v_mfma_f32_16x16x32_bf16 v[90:93], v[146:149], v[226:229], v[90:93]
	v_mfma_f32_16x16x32_bf16 v[78:81], v[138:141], v[234:237], v[78:81]
	v_mfma_f32_16x16x32_bf16 v[74:77], v[146:149], v[234:237], v[74:77]
	v_mfma_f32_16x16x32_bf16 v[118:121], v[150:153], v[166:169], 0
	v_mfma_f32_16x16x32_bf16 v[114:117], v[158:161], v[166:169], 0
	v_mfma_f32_16x16x32_bf16 v[102:105], v[150:153], v[214:217], 0
	v_mfma_f32_16x16x32_bf16 v[98:101], v[158:161], v[214:217], 0
	v_mfma_f32_16x16x32_bf16 v[86:89], v[150:153], v[222:225], 0
	v_mfma_f32_16x16x32_bf16 v[82:85], v[158:161], v[222:225], 0
	v_mfma_f32_16x16x32_bf16 v[70:73], v[150:153], v[230:233], 0
	v_mfma_f32_16x16x32_bf16 v[66:69], v[158:161], v[230:233], 0
	v_mfma_f32_16x16x32_bf16 v[118:121], v[154:157], v[210:213], v[118:121]
	v_mfma_f32_16x16x32_bf16 v[114:117], v[162:165], v[210:213], v[114:117]
	v_mfma_f32_16x16x32_bf16 v[102:105], v[154:157], v[218:221], v[102:105]
	v_mfma_f32_16x16x32_bf16 v[98:101], v[162:165], v[218:221], v[98:101]
	v_mfma_f32_16x16x32_bf16 v[86:89], v[154:157], v[226:229], v[86:89]
	v_mfma_f32_16x16x32_bf16 v[82:85], v[162:165], v[226:229], v[82:85]
	v_mfma_f32_16x16x32_bf16 v[70:73], v[154:157], v[234:237], v[70:73]
	v_mfma_f32_16x16x32_bf16 v[66:69], v[162:165], v[234:237], v[66:69]
	s_barrier
	ds_read_b128 v[166:169], v203 offset:16384
	ds_read_b128 v[210:213], v203 offset:17408
	ds_read_b128 v[214:217], v203 offset:18432
	ds_read_b128 v[218:221], v203 offset:19456
	ds_read_b128 v[222:225], v203 offset:20480
	ds_read_b128 v[226:229], v203 offset:21504
	ds_read_b128 v[230:233], v203 offset:22528
	ds_read_b128 v[234:237], v203 offset:23552
	s_mov_b32 m0, s17
	s_nop 0
	global_load_lds_dwordx4 v172, s[70:71]
	s_add_u32 s86, s70, 0x100000
	s_mov_b32 m0, s19
	s_nop 0
	global_load_lds_dwordx4 v174, s[70:71]
	s_addc_u32 s87, s71, 0
	s_mov_b32 m0, s23
	s_nop 0
	global_load_lds_dwordx4 v172, s[86:87]
	s_mov_b32 m0, s26
	s_nop 0
	global_load_lds_dwordx4 v174, s[86:87]
	s_mov_b32 m0, s15
	s_nop 0
	global_load_lds_dwordx4 v1, s[72:73]
	s_mov_b32 m0, s27
	s_nop 0
	global_load_lds_dwordx4 v173, s[72:73]
	s_waitcnt vmcnt(8) lgkmcnt(0)
	s_barrier
	v_mfma_f32_16x16x32_bf16 v[62:65], v[134:137], v[166:169], 0
	v_mfma_f32_16x16x32_bf16 v[58:61], v[142:145], v[166:169], 0
	v_mfma_f32_16x16x32_bf16 v[46:49], v[134:137], v[214:217], 0
	v_mfma_f32_16x16x32_bf16 v[42:45], v[142:145], v[214:217], 0
	v_mfma_f32_16x16x32_bf16 v[30:33], v[134:137], v[222:225], 0
	v_mfma_f32_16x16x32_bf16 v[26:29], v[142:145], v[222:225], 0
	v_mfma_f32_16x16x32_bf16 v[14:17], v[134:137], v[230:233], 0
	v_mfma_f32_16x16x32_bf16 v[10:13], v[142:145], v[230:233], 0
	v_mfma_f32_16x16x32_bf16 v[62:65], v[138:141], v[210:213], v[62:65]
	v_mfma_f32_16x16x32_bf16 v[58:61], v[146:149], v[210:213], v[58:61]
	v_mfma_f32_16x16x32_bf16 v[46:49], v[138:141], v[218:221], v[46:49]
	v_mfma_f32_16x16x32_bf16 v[42:45], v[146:149], v[218:221], v[42:45]
	v_mfma_f32_16x16x32_bf16 v[30:33], v[138:141], v[226:229], v[30:33]
	v_mfma_f32_16x16x32_bf16 v[26:29], v[146:149], v[226:229], v[26:29]
	v_mfma_f32_16x16x32_bf16 v[14:17], v[138:141], v[234:237], v[14:17]
	v_mfma_f32_16x16x32_bf16 v[10:13], v[146:149], v[234:237], v[10:13]
	v_mfma_f32_16x16x32_bf16 v[54:57], v[150:153], v[166:169], 0
	v_mfma_f32_16x16x32_bf16 v[50:53], v[158:161], v[166:169], 0
	v_mfma_f32_16x16x32_bf16 v[38:41], v[150:153], v[214:217], 0
	v_mfma_f32_16x16x32_bf16 v[34:37], v[158:161], v[214:217], 0
	v_mfma_f32_16x16x32_bf16 v[22:25], v[150:153], v[222:225], 0
	v_mfma_f32_16x16x32_bf16 v[18:21], v[158:161], v[222:225], 0
	v_mfma_f32_16x16x32_bf16 v[6:9], v[150:153], v[230:233], 0
	v_mfma_f32_16x16x32_bf16 v[2:5], v[158:161], v[230:233], 0
	v_mfma_f32_16x16x32_bf16 v[54:57], v[154:157], v[210:213], v[54:57]
	v_mfma_f32_16x16x32_bf16 v[50:53], v[162:165], v[210:213], v[50:53]
	v_mfma_f32_16x16x32_bf16 v[38:41], v[154:157], v[218:221], v[38:41]
	v_mfma_f32_16x16x32_bf16 v[34:37], v[162:165], v[218:221], v[34:37]
	v_mfma_f32_16x16x32_bf16 v[22:25], v[154:157], v[226:229], v[22:25]
	v_mfma_f32_16x16x32_bf16 v[18:21], v[162:165], v[226:229], v[18:21]
	v_mfma_f32_16x16x32_bf16 v[6:9], v[154:157], v[234:237], v[6:9]
	v_mfma_f32_16x16x32_bf16 v[2:5], v[162:165], v[234:237], v[2:5]
	s_barrier
; #define PG8_STAGE(bufoff, gbase, voff) do { if constexpr (VAR != 1 && VAR != 3) { _Pragma("unroll") for (int _i = 0; _i < 2; ++_i) \
;         asm volatile("s_mov_b32 m0, %2\n\ts_nop 0\n\tglobal_load_lds_dwordx4 %0, %1" :: "v"((voff)[_i]), "s"((const char*)(gbase)), "s"(ldsbase + (unsigned)((bufoff) + _i * 8192)) : "memory", "m0"); } } while (0)
; #define PG8_LDA(dst, b, h) do { if constexpr (VAR < 2) _Pragma("unroll") for (int m = 0; m < 4; ++m) _Pragma("unroll") for (int k = 0; k < 2; ++k) dst[m][k] = *(const LAS bf16x8*)(lds + PG8_SA(b, h) + aoff + m * 2048 + k * 1024); } while (0)
; #define PG8_LDB(dst, b, h) do { if constexpr (VAR < 2) _Pragma("unroll") for (int n = 0; n < 2; ++n) _Pragma("unroll") for (int k = 0; k < 2; ++k) dst[n][k] = *(const LAS bf16x8*)(lds + PG8_SB(b, h) + boff + n * 2048 + k * 1024); } while (0)
; #define PG8_WAIT_V(n) asm volatile("s_waitcnt vmcnt(" #n ")" ::: "memory")
; #define PG8_WAIT_L(n) asm volatile("s_waitcnt lgkmcnt(" #n ")" ::: "memory")
;     ...
;         for (int t = 0; t < nt; t += 2) {
;             const bool last = (t == nt - 2);
;             const char* a1 = cA + (size_t)(t + 1) * kstep;
;             const char* a2 = last ? nA : cA + (size_t)(t + 2) * kstep; const char* b2 = last ? nB : cB + (size_t)(t + 2) * kstep;
;             const char* a3 = a2 + kstep; const char* b3 = b2 + kstep;
;             PG8_LDB(B0, 0, 0); PG8_LDB(B1, 0, 1); PG8_SCHED; PG8_LDA(At, 0, 0); PG8_STAGE(PG8_SA(1, 1), a1 + hstepA, voffA);
;             PG8_WAIT_V(8); PG8_WAIT_L(0); PG8_BAR; PG8_MMA(0, 0, At, B0); PG8_MMA(0, 1, At, B1); PG8_BAR; PG8_SCHED;
;             PG8_LDA(At, 0, 1); PG8_STAGE(PG8_SB(0, 0), b2, voffB); PG8_STAGE(PG8_SB(0, 1), b2 + hstepB, voffB); PG8_STAGE(PG8_SA(0, 0), a2, voffA);
;             PG8_WAIT_V(8); PG8_WAIT_L(0); PG8_BAR; PG8_MMA(1, 0, At, B0); PG8_MMA(1, 1, At, B1); PG8_BAR; PG8_SCHED;
;             PG8_LDB(B0, 1, 0); PG8_LDB(B1, 1, 1); PG8_SCHED; PG8_LDA(At, 1, 0); PG8_STAGE(PG8_SA(0, 1), a2 + hstepA, voffA);
;             PG8_WAIT_V(8); PG8_WAIT_L(0); PG8_BAR; PG8_MMA(0, 0, At, B0); PG8_MMA(0, 1, At, B1); PG8_BAR; PG8_SCHED;
;             PG8_LDA(At, 1, 1); PG8_STAGE(PG8_SB(1, 0), b3, voffB); PG8_STAGE(PG8_SB(1, 1), b3 + hstepB, voffB); PG8_STAGE(PG8_SA(1, 0), a3, voffA);
;             PG8_WAIT_V(8); PG8_WAIT_L(0); PG8_BAR; PG8_MMA(1, 0, At, B0); PG8_MMA(1, 1, At, B1); PG8_BAR; PG8_SCHED;
	ds_read_b128 v[134:137], v204
	ds_read_b128 v[138:141], v204 offset:1024
	ds_read_b128 v[142:145], v204 offset:2048
	ds_read_b128 v[146:149], v204 offset:3072
	ds_read_b128 v[150:153], v205
	ds_read_b128 v[154:157], v205 offset:1024
	ds_read_b128 v[158:161], v205 offset:2048
	ds_read_b128 v[162:165], v205 offset:3072
	ds_read_b128 v[166:169], v203 offset:32768
	ds_read_b128 v[210:213], v203 offset:33792
	ds_read_b128 v[214:217], v203 offset:34816
	ds_read_b128 v[218:221], v203 offset:35840
	ds_read_b128 v[222:225], v203 offset:36864
	ds_read_b128 v[226:229], v203 offset:37888
	ds_read_b128 v[230:233], v203 offset:38912
	ds_read_b128 v[234:237], v203 offset:39936
	s_add_u32 s72, s72, 0x104000
	s_addc_u32 s73, s73, 0
	s_mov_b32 m0, s28
	s_nop 0
	global_load_lds_dwordx4 v1, s[72:73]
	s_mov_b32 m0, s29
	s_nop 0
	global_load_lds_dwordx4 v173, s[72:73]
	s_waitcnt vmcnt(8) lgkmcnt(0)
	s_barrier
	v_mfma_f32_16x16x32_bf16 v[126:129], v[134:137], v[166:169], v[126:129]
	v_mfma_f32_16x16x32_bf16 v[122:125], v[142:145], v[166:169], v[122:125]
	v_mfma_f32_16x16x32_bf16 v[110:113], v[134:137], v[214:217], v[110:113]
	v_mfma_f32_16x16x32_bf16 v[106:109], v[142:145], v[214:217], v[106:109]
	v_mfma_f32_16x16x32_bf16 v[94:97], v[134:137], v[222:225], v[94:97]
	v_mfma_f32_16x16x32_bf16 v[90:93], v[142:145], v[222:225], v[90:93]
	v_mfma_f32_16x16x32_bf16 v[78:81], v[134:137], v[230:233], v[78:81]
	v_mfma_f32_16x16x32_bf16 v[74:77], v[142:145], v[230:233], v[74:77]
	v_mfma_f32_16x16x32_bf16 v[126:129], v[138:141], v[210:213], v[126:129]
	v_mfma_f32_16x16x32_bf16 v[122:125], v[146:149], v[210:213], v[122:125]
	v_mfma_f32_16x16x32_bf16 v[110:113], v[138:141], v[218:221], v[110:113]
	v_mfma_f32_16x16x32_bf16 v[106:109], v[146:149], v[218:221], v[106:109]
	v_mfma_f32_16x16x32_bf16 v[94:97], v[138:141], v[226:229], v[94:97]
	v_mfma_f32_16x16x32_bf16 v[90:93], v[146:149], v[226:229], v[90:93]
	v_mfma_f32_16x16x32_bf16 v[78:81], v[138:141], v[234:237], v[78:81]
	v_mfma_f32_16x16x32_bf16 v[74:77], v[146:149], v[234:237], v[74:77]
	v_mfma_f32_16x16x32_bf16 v[118:121], v[150:153], v[166:169], v[118:121]
	v_mfma_f32_16x16x32_bf16 v[114:117], v[158:161], v[166:169], v[114:117]
	v_mfma_f32_16x16x32_bf16 v[102:105], v[150:153], v[214:217], v[102:105]
	v_mfma_f32_16x16x32_bf16 v[98:101], v[158:161], v[214:217], v[98:101]
	v_mfma_f32_16x16x32_bf16 v[86:89], v[150:153], v[222:225], v[86:89]
	v_mfma_f32_16x16x32_bf16 v[82:85], v[158:161], v[222:225], v[82:85]
	v_mfma_f32_16x16x32_bf16 v[70:73], v[150:153], v[230:233], v[70:73]
	v_mfma_f32_16x16x32_bf16 v[66:69], v[158:161], v[230:233], v[66:69]
	v_mfma_f32_16x16x32_bf16 v[118:121], v[154:157], v[210:213], v[118:121]
	v_mfma_f32_16x16x32_bf16 v[114:117], v[162:165], v[210:213], v[114:117]
	v_mfma_f32_16x16x32_bf16 v[102:105], v[154:157], v[218:221], v[102:105]
	v_mfma_f32_16x16x32_bf16 v[98:101], v[162:165], v[218:221], v[98:101]
	v_mfma_f32_16x16x32_bf16 v[86:89], v[154:157], v[226:229], v[86:89]
	v_mfma_f32_16x16x32_bf16 v[82:85], v[162:165], v[226:229], v[82:85]
	v_mfma_f32_16x16x32_bf16 v[70:73], v[154:157], v[234:237], v[70:73]
	v_mfma_f32_16x16x32_bf16 v[66:69], v[162:165], v[234:237], v[66:69]
	s_barrier
	ds_read_b128 v[166:169], v203 offset:49152
	ds_read_b128 v[210:213], v203 offset:50176
	ds_read_b128 v[214:217], v203 offset:51200
	ds_read_b128 v[218:221], v203 offset:52224
	ds_read_b128 v[222:225], v203 offset:53248
	ds_read_b128 v[226:229], v203 offset:54272
	ds_read_b128 v[230:233], v203 offset:55296
	ds_read_b128 v[234:237], v203 offset:56320
	s_add_u32 s72, s70, 0x80
	s_addc_u32 s73, s71, 0
	s_mov_b32 m0, s33
	s_nop 0
	global_load_lds_dwordx4 v172, s[72:73]
	s_add_u32 s70, s70, 0x100080
	s_mov_b32 m0, s35
	s_nop 0
	global_load_lds_dwordx4 v174, s[72:73]
	s_addc_u32 s71, s71, 0
	s_mov_b32 m0, s75
	s_nop 0
	global_load_lds_dwordx4 v172, s[70:71]
	s_mov_b32 m0, s76
	s_nop 0
	global_load_lds_dwordx4 v174, s[70:71]
	s_mov_b32 m0, s67
	s_nop 0
	global_load_lds_dwordx4 v1, s[68:69]
	s_mov_b32 m0, s74
	s_nop 0
	global_load_lds_dwordx4 v173, s[68:69]
	s_waitcnt vmcnt(8) lgkmcnt(0)
	s_barrier
	v_mfma_f32_16x16x32_bf16 v[62:65], v[134:137], v[166:169], v[62:65]
	v_mfma_f32_16x16x32_bf16 v[58:61], v[142:145], v[166:169], v[58:61]
	v_mfma_f32_16x16x32_bf16 v[46:49], v[134:137], v[214:217], v[46:49]
	v_mfma_f32_16x16x32_bf16 v[42:45], v[142:145], v[214:217], v[42:45]
	v_mfma_f32_16x16x32_bf16 v[30:33], v[134:137], v[222:225], v[30:33]
	v_mfma_f32_16x16x32_bf16 v[26:29], v[142:145], v[222:225], v[26:29]
	v_mfma_f32_16x16x32_bf16 v[14:17], v[134:137], v[230:233], v[14:17]
	v_mfma_f32_16x16x32_bf16 v[10:13], v[142:145], v[230:233], v[10:13]
	v_mfma_f32_16x16x32_bf16 v[62:65], v[138:141], v[210:213], v[62:65]
	v_mfma_f32_16x16x32_bf16 v[58:61], v[146:149], v[210:213], v[58:61]
	v_mfma_f32_16x16x32_bf16 v[46:49], v[138:141], v[218:221], v[46:49]
	v_mfma_f32_16x16x32_bf16 v[42:45], v[146:149], v[218:221], v[42:45]
	v_mfma_f32_16x16x32_bf16 v[30:33], v[138:141], v[226:229], v[30:33]
	v_mfma_f32_16x16x32_bf16 v[26:29], v[146:149], v[226:229], v[26:29]
	v_mfma_f32_16x16x32_bf16 v[14:17], v[138:141], v[234:237], v[14:17]
	v_mfma_f32_16x16x32_bf16 v[10:13], v[146:149], v[234:237], v[10:13]
	v_mfma_f32_16x16x32_bf16 v[54:57], v[150:153], v[166:169], v[54:57]
	v_mfma_f32_16x16x32_bf16 v[50:53], v[158:161], v[166:169], v[50:53]
	v_mfma_f32_16x16x32_bf16 v[38:41], v[150:153], v[214:217], v[38:41]
	v_mfma_f32_16x16x32_bf16 v[34:37], v[158:161], v[214:217], v[34:37]
	v_mfma_f32_16x16x32_bf16 v[22:25], v[150:153], v[222:225], v[22:25]
	v_mfma_f32_16x16x32_bf16 v[18:21], v[158:161], v[222:225], v[18:21]
	v_mfma_f32_16x16x32_bf16 v[6:9], v[150:153], v[230:233], v[6:9]
	v_mfma_f32_16x16x32_bf16 v[2:5], v[158:161], v[230:233], v[2:5]
	v_mfma_f32_16x16x32_bf16 v[54:57], v[154:157], v[210:213], v[54:57]
	v_mfma_f32_16x16x32_bf16 v[50:53], v[162:165], v[210:213], v[50:53]
	v_mfma_f32_16x16x32_bf16 v[38:41], v[154:157], v[218:221], v[38:41]
	v_mfma_f32_16x16x32_bf16 v[34:37], v[162:165], v[218:221], v[34:37]
	v_mfma_f32_16x16x32_bf16 v[22:25], v[154:157], v[226:229], v[22:25]
	v_mfma_f32_16x16x32_bf16 v[18:21], v[162:165], v[226:229], v[18:21]
	v_mfma_f32_16x16x32_bf16 v[6:9], v[154:157], v[234:237], v[6:9]
	v_mfma_f32_16x16x32_bf16 v[2:5], v[162:165], v[234:237], v[2:5]
	s_barrier
	s_add_i32 s85, s85, 2
	s_add_u32 s25, s25, 0x100
	s_addc_u32 s39, s39, 0
	s_add_u32 s59, s59, 0x100
	s_addc_u32 s84, s84, 0
	s_add_u32 s6, s6, 0x100
	s_addc_u32 s7, s7, 0
	s_cmp_gt_u32 s85, 61
	s_cbranch_scc0 .LBB0_892
	s_branch .Lmy_kexit_6
; #define PG8_STAGE(bufoff, gbase, voff) do { if constexpr (VAR != 1 && VAR != 3) { _Pragma("unroll") for (int _i = 0; _i < 2; ++_i) \
;         asm volatile("s_mov_b32 m0, %2\n\ts_nop 0\n\tglobal_load_lds_dwordx4 %0, %1" :: "v"((voff)[_i]), "s"((const char*)(gbase)), "s"(ldsbase + (unsigned)((bufoff) + _i * 8192)) : "memory", "m0"); } } while (0)
; #define PG8_LDA(dst, b, h) do { if constexpr (VAR < 2) _Pragma("unroll") for (int m = 0; m < 4; ++m) _Pragma("unroll") for (int k = 0; k < 2; ++k) dst[m][k] = *(const LAS bf16x8*)(lds + PG8_SA(b, h) + aoff + m * 2048 + k * 1024); } while (0)
; #define PG8_LDB(dst, b, h) do { if constexpr (VAR < 2) _Pragma("unroll") for (int n = 0; n < 2; ++n) _Pragma("unroll") for (int k = 0; k < 2; ++k) dst[n][k] = *(const LAS bf16x8*)(lds + PG8_SB(b, h) + boff + n * 2048 + k * 1024); } while (0)
; #define PG8_WAIT_V(n) asm volatile("s_waitcnt vmcnt(" #n ")" ::: "memory")
; #define PG8_WAIT_L(n) asm volatile("s_waitcnt lgkmcnt(" #n ")" ::: "memory")
; #define PG8_BAR do { if constexpr (VAR != 3) __builtin_amdgcn_s_barrier(); } while (0)
; #define PG8_SCHED __builtin_amdgcn_sched_barrier(0)
;     ...
;             const bool last = (t == nt - 2);
;             const char* a1 = cA + (size_t)(t + 1) * kstep;
;             const char* a2 = last ? nA : cA + (size_t)(t + 2) * kstep; const char* b2 = last ? nB : cB + (size_t)(t + 2) * kstep;
;             const char* a3 = a2 + kstep; const char* b3 = b2 + kstep;
;             PG8_LDB(B0, 0, 0); PG8_LDB(B1, 0, 1); PG8_SCHED; PG8_LDA(At, 0, 0); PG8_STAGE(PG8_SA(1, 1), a1 + hstepA, voffA);
;             PG8_WAIT_V(8); PG8_WAIT_L(0); PG8_BAR; PG8_MMA(0, 0, At, B0); PG8_MMA(0, 1, At, B1); PG8_BAR; PG8_SCHED;
;             PG8_LDA(At, 0, 1); PG8_STAGE(PG8_SB(0, 0), b2, voffB); PG8_STAGE(PG8_SB(0, 1), b2 + hstepB, voffB); PG8_STAGE(PG8_SA(0, 0), a2, voffA);
;             PG8_WAIT_V(8); PG8_WAIT_L(0); PG8_BAR; PG8_MMA(1, 0, At, B0); PG8_MMA(1, 1, At, B1); PG8_BAR; PG8_SCHED;
.LBB0_892:
	ds_read_b128 v[134:137], v201
	ds_read_b128 v[138:141], v201 offset:1024
	ds_read_b128 v[142:145], v201 offset:2048
	ds_read_b128 v[146:149], v201 offset:3072
	ds_read_b128 v[150:153], v202
	ds_read_b128 v[154:157], v202 offset:1024
	ds_read_b128 v[158:161], v202 offset:2048
	ds_read_b128 v[162:165], v202 offset:3072
	s_cmp_eq_u32 s85, 60
	s_cselect_b32 s72, s24, s25
	s_cselect_b32 s73, s1, s39
	s_cselect_b32 s70, s60, s59
	s_cselect_b32 s71, s61, s84
	s_add_u32 s68, s72, 0x80
	s_addc_u32 s69, s73, 0
	ds_read_b128 v[166:169], v203
	ds_read_b128 v[210:213], v203 offset:1024
	ds_read_b128 v[214:217], v203 offset:2048
	ds_read_b128 v[218:221], v203 offset:3072
	ds_read_b128 v[222:225], v203 offset:4096
	ds_read_b128 v[226:229], v203 offset:5120
	ds_read_b128 v[230:233], v203 offset:6144
	ds_read_b128 v[234:237], v203 offset:7168
	s_mov_b32 m0, s77
	s_nop 0
	global_load_lds_dwordx4 v1, s[6:7]
	s_mov_b32 m0, s79
	s_nop 0
	global_load_lds_dwordx4 v173, s[6:7]
	s_waitcnt vmcnt(8) lgkmcnt(0)
	s_barrier
	v_mfma_f32_16x16x32_bf16 v[126:129], v[134:137], v[166:169], v[126:129]
	v_mfma_f32_16x16x32_bf16 v[122:125], v[142:145], v[166:169], v[122:125]
	v_mfma_f32_16x16x32_bf16 v[110:113], v[134:137], v[214:217], v[110:113]
	v_mfma_f32_16x16x32_bf16 v[106:109], v[142:145], v[214:217], v[106:109]
	v_mfma_f32_16x16x32_bf16 v[94:97], v[134:137], v[222:225], v[94:97]
	v_mfma_f32_16x16x32_bf16 v[90:93], v[142:145], v[222:225], v[90:93]
	v_mfma_f32_16x16x32_bf16 v[78:81], v[134:137], v[230:233], v[78:81]
	v_mfma_f32_16x16x32_bf16 v[74:77], v[142:145], v[230:233], v[74:77]
	v_mfma_f32_16x16x32_bf16 v[126:129], v[138:141], v[210:213], v[126:129]
	v_mfma_f32_16x16x32_bf16 v[122:125], v[146:149], v[210:213], v[122:125]
	v_mfma_f32_16x16x32_bf16 v[110:113], v[138:141], v[218:221], v[110:113]
	v_mfma_f32_16x16x32_bf16 v[106:109], v[146:149], v[218:221], v[106:109]
	v_mfma_f32_16x16x32_bf16 v[94:97], v[138:141], v[226:229], v[94:97]
	v_mfma_f32_16x16x32_bf16 v[90:93], v[146:149], v[226:229], v[90:93]
	v_mfma_f32_16x16x32_bf16 v[78:81], v[138:141], v[234:237], v[78:81]
	v_mfma_f32_16x16x32_bf16 v[74:77], v[146:149], v[234:237], v[74:77]
	v_mfma_f32_16x16x32_bf16 v[118:121], v[150:153], v[166:169], v[118:121]
	v_mfma_f32_16x16x32_bf16 v[114:117], v[158:161], v[166:169], v[114:117]
	v_mfma_f32_16x16x32_bf16 v[102:105], v[150:153], v[214:217], v[102:105]
	v_mfma_f32_16x16x32_bf16 v[98:101], v[158:161], v[214:217], v[98:101]
	v_mfma_f32_16x16x32_bf16 v[86:89], v[150:153], v[222:225], v[86:89]
	v_mfma_f32_16x16x32_bf16 v[82:85], v[158:161], v[222:225], v[82:85]
	v_mfma_f32_16x16x32_bf16 v[70:73], v[150:153], v[230:233], v[70:73]
	v_mfma_f32_16x16x32_bf16 v[66:69], v[158:161], v[230:233], v[66:69]
	v_mfma_f32_16x16x32_bf16 v[118:121], v[154:157], v[210:213], v[118:121]
	v_mfma_f32_16x16x32_bf16 v[114:117], v[162:165], v[210:213], v[114:117]
	v_mfma_f32_16x16x32_bf16 v[102:105], v[154:157], v[218:221], v[102:105]
	v_mfma_f32_16x16x32_bf16 v[98:101], v[162:165], v[218:221], v[98:101]
	v_mfma_f32_16x16x32_bf16 v[86:89], v[154:157], v[226:229], v[86:89]
	v_mfma_f32_16x16x32_bf16 v[82:85], v[162:165], v[226:229], v[82:85]
	v_mfma_f32_16x16x32_bf16 v[70:73], v[154:157], v[234:237], v[70:73]
	v_mfma_f32_16x16x32_bf16 v[66:69], v[162:165], v[234:237], v[66:69]
	s_barrier
	ds_read_b128 v[166:169], v203 offset:16384
	ds_read_b128 v[210:213], v203 offset:17408
	ds_read_b128 v[214:217], v203 offset:18432
	ds_read_b128 v[218:221], v203 offset:19456
	ds_read_b128 v[222:225], v203 offset:20480
	ds_read_b128 v[226:229], v203 offset:21504
	ds_read_b128 v[230:233], v203 offset:22528
	ds_read_b128 v[234:237], v203 offset:23552
	s_mov_b32 m0, s17
	s_nop 0
	global_load_lds_dwordx4 v172, s[70:71]
	s_add_u32 s86, s70, 0x100000
	s_mov_b32 m0, s19
	s_nop 0
	global_load_lds_dwordx4 v174, s[70:71]
	s_addc_u32 s87, s71, 0
	s_mov_b32 m0, s23
	s_nop 0
	global_load_lds_dwordx4 v172, s[86:87]
	s_mov_b32 m0, s26
	s_nop 0
	global_load_lds_dwordx4 v174, s[86:87]
	s_mov_b32 m0, s15
	s_nop 0
	global_load_lds_dwordx4 v1, s[72:73]
	s_mov_b32 m0, s27
	s_nop 0
	global_load_lds_dwordx4 v173, s[72:73]
	s_waitcnt vmcnt(8) lgkmcnt(0)
	s_barrier
	v_mfma_f32_16x16x32_bf16 v[62:65], v[134:137], v[166:169], v[62:65]
	v_mfma_f32_16x16x32_bf16 v[58:61], v[142:145], v[166:169], v[58:61]
	v_mfma_f32_16x16x32_bf16 v[46:49], v[134:137], v[214:217], v[46:49]
	v_mfma_f32_16x16x32_bf16 v[42:45], v[142:145], v[214:217], v[42:45]
	v_mfma_f32_16x16x32_bf16 v[30:33], v[134:137], v[222:225], v[30:33]
	v_mfma_f32_16x16x32_bf16 v[26:29], v[142:145], v[222:225], v[26:29]
	v_mfma_f32_16x16x32_bf16 v[14:17], v[134:137], v[230:233], v[14:17]
	v_mfma_f32_16x16x32_bf16 v[10:13], v[142:145], v[230:233], v[10:13]
	v_mfma_f32_16x16x32_bf16 v[62:65], v[138:141], v[210:213], v[62:65]
	v_mfma_f32_16x16x32_bf16 v[58:61], v[146:149], v[210:213], v[58:61]
	v_mfma_f32_16x16x32_bf16 v[46:49], v[138:141], v[218:221], v[46:49]
	v_mfma_f32_16x16x32_bf16 v[42:45], v[146:149], v[218:221], v[42:45]
	v_mfma_f32_16x16x32_bf16 v[30:33], v[138:141], v[226:229], v[30:33]
	v_mfma_f32_16x16x32_bf16 v[26:29], v[146:149], v[226:229], v[26:29]
	v_mfma_f32_16x16x32_bf16 v[14:17], v[138:141], v[234:237], v[14:17]
	v_mfma_f32_16x16x32_bf16 v[10:13], v[146:149], v[234:237], v[10:13]
	v_mfma_f32_16x16x32_bf16 v[54:57], v[150:153], v[166:169], v[54:57]
	v_mfma_f32_16x16x32_bf16 v[50:53], v[158:161], v[166:169], v[50:53]
	v_mfma_f32_16x16x32_bf16 v[38:41], v[150:153], v[214:217], v[38:41]
	v_mfma_f32_16x16x32_bf16 v[34:37], v[158:161], v[214:217], v[34:37]
	v_mfma_f32_16x16x32_bf16 v[22:25], v[150:153], v[222:225], v[22:25]
	v_mfma_f32_16x16x32_bf16 v[18:21], v[158:161], v[222:225], v[18:21]
	v_mfma_f32_16x16x32_bf16 v[6:9], v[150:153], v[230:233], v[6:9]
	v_mfma_f32_16x16x32_bf16 v[2:5], v[158:161], v[230:233], v[2:5]
	v_mfma_f32_16x16x32_bf16 v[54:57], v[154:157], v[210:213], v[54:57]
	v_mfma_f32_16x16x32_bf16 v[50:53], v[162:165], v[210:213], v[50:53]
	v_mfma_f32_16x16x32_bf16 v[38:41], v[154:157], v[218:221], v[38:41]
	v_mfma_f32_16x16x32_bf16 v[34:37], v[162:165], v[218:221], v[34:37]
	v_mfma_f32_16x16x32_bf16 v[22:25], v[154:157], v[226:229], v[22:25]
	v_mfma_f32_16x16x32_bf16 v[18:21], v[162:165], v[226:229], v[18:21]
	v_mfma_f32_16x16x32_bf16 v[6:9], v[154:157], v[234:237], v[6:9]
	v_mfma_f32_16x16x32_bf16 v[2:5], v[162:165], v[234:237], v[2:5]
	s_barrier
; #define PG8_STAGE(bufoff, gbase, voff) do { if constexpr (VAR != 1 && VAR != 3) { _Pragma("unroll") for (int _i = 0; _i < 2; ++_i) \
;         asm volatile("s_mov_b32 m0, %2\n\ts_nop 0\n\tglobal_load_lds_dwordx4 %0, %1" :: "v"((voff)[_i]), "s"((const char*)(gbase)), "s"(ldsbase + (unsigned)((bufoff) + _i * 8192)) : "memory", "m0"); } } while (0)
; #define PG8_LDA(dst, b, h) do { if constexpr (VAR < 2) _Pragma("unroll") for (int m = 0; m < 4; ++m) _Pragma("unroll") for (int k = 0; k < 2; ++k) dst[m][k] = *(const LAS bf16x8*)(lds + PG8_SA(b, h) + aoff + m * 2048 + k * 1024); } while (0)
; #define PG8_LDB(dst, b, h) do { if constexpr (VAR < 2) _Pragma("unroll") for (int n = 0; n < 2; ++n) _Pragma("unroll") for (int k = 0; k < 2; ++k) dst[n][k] = *(const LAS bf16x8*)(lds + PG8_SB(b, h) + boff + n * 2048 + k * 1024); } while (0)
; #define PG8_WAIT_V(n) asm volatile("s_waitcnt vmcnt(" #n ")" ::: "memory")
; #define PG8_WAIT_L(n) asm volatile("s_waitcnt lgkmcnt(" #n ")" ::: "memory")
;     ...
;         for (int t = 0; t < nt; t += 2) {
;             const bool last = (t == nt - 2);
;             const char* a1 = cA + (size_t)(t + 1) * kstep;
;             const char* a2 = last ? nA : cA + (size_t)(t + 2) * kstep; const char* b2 = last ? nB : cB + (size_t)(t + 2) * kstep;
;             const char* a3 = a2 + kstep; const char* b3 = b2 + kstep;
;             PG8_LDB(B0, 0, 0); PG8_LDB(B1, 0, 1); PG8_SCHED; PG8_LDA(At, 0, 0); PG8_STAGE(PG8_SA(1, 1), a1 + hstepA, voffA);
;             PG8_WAIT_V(8); PG8_WAIT_L(0); PG8_BAR; PG8_MMA(0, 0, At, B0); PG8_MMA(0, 1, At, B1); PG8_BAR; PG8_SCHED;
;             PG8_LDA(At, 0, 1); PG8_STAGE(PG8_SB(0, 0), b2, voffB); PG8_STAGE(PG8_SB(0, 1), b2 + hstepB, voffB); PG8_STAGE(PG8_SA(0, 0), a2, voffA);
;             PG8_WAIT_V(8); PG8_WAIT_L(0); PG8_BAR; PG8_MMA(1, 0, At, B0); PG8_MMA(1, 1, At, B1); PG8_BAR; PG8_SCHED;
;             PG8_LDB(B0, 1, 0); PG8_LDB(B1, 1, 1); PG8_SCHED; PG8_LDA(At, 1, 0); PG8_STAGE(PG8_SA(0, 1), a2 + hstepA, voffA);
;             PG8_WAIT_V(8); PG8_WAIT_L(0); PG8_BAR; PG8_MMA(0, 0, At, B0); PG8_MMA(0, 1, At, B1); PG8_BAR; PG8_SCHED;
;             PG8_LDA(At, 1, 1); PG8_STAGE(PG8_SB(1, 0), b3, voffB); PG8_STAGE(PG8_SB(1, 1), b3 + hstepB, voffB); PG8_STAGE(PG8_SA(1, 0), a3, voffA);
;             PG8_WAIT_V(8); PG8_WAIT_L(0); PG8_BAR; PG8_MMA(1, 0, At, B0); PG8_MMA(1, 1, At, B1); PG8_BAR; PG8_SCHED;
	ds_read_b128 v[134:137], v204
	ds_read_b128 v[138:141], v204 offset:1024
	ds_read_b128 v[142:145], v204 offset:2048
	ds_read_b128 v[146:149], v204 offset:3072
	ds_read_b128 v[150:153], v205
	ds_read_b128 v[154:157], v205 offset:1024
	ds_read_b128 v[158:161], v205 offset:2048
	ds_read_b128 v[162:165], v205 offset:3072
	ds_read_b128 v[166:169], v203 offset:32768
	ds_read_b128 v[210:213], v203 offset:33792
	ds_read_b128 v[214:217], v203 offset:34816
	ds_read_b128 v[218:221], v203 offset:35840
	ds_read_b128 v[222:225], v203 offset:36864
	ds_read_b128 v[226:229], v203 offset:37888
	ds_read_b128 v[230:233], v203 offset:38912
	ds_read_b128 v[234:237], v203 offset:39936
	s_add_u32 s72, s72, 0x104000
	s_addc_u32 s73, s73, 0
	s_mov_b32 m0, s28
	s_nop 0
	global_load_lds_dwordx4 v1, s[72:73]
	s_mov_b32 m0, s29
	s_nop 0
	global_load_lds_dwordx4 v173, s[72:73]
	s_waitcnt vmcnt(8) lgkmcnt(0)
	s_barrier
	v_mfma_f32_16x16x32_bf16 v[126:129], v[134:137], v[166:169], v[126:129]
	v_mfma_f32_16x16x32_bf16 v[122:125], v[142:145], v[166:169], v[122:125]
	v_mfma_f32_16x16x32_bf16 v[110:113], v[134:137], v[214:217], v[110:113]
	v_mfma_f32_16x16x32_bf16 v[106:109], v[142:145], v[214:217], v[106:109]
	v_mfma_f32_16x16x32_bf16 v[94:97], v[134:137], v[222:225], v[94:97]
	v_mfma_f32_16x16x32_bf16 v[90:93], v[142:145], v[222:225], v[90:93]
	v_mfma_f32_16x16x32_bf16 v[78:81], v[134:137], v[230:233], v[78:81]
	v_mfma_f32_16x16x32_bf16 v[74:77], v[142:145], v[230:233], v[74:77]
	v_mfma_f32_16x16x32_bf16 v[126:129], v[138:141], v[210:213], v[126:129]
	v_mfma_f32_16x16x32_bf16 v[122:125], v[146:149], v[210:213], v[122:125]
	v_mfma_f32_16x16x32_bf16 v[110:113], v[138:141], v[218:221], v[110:113]
	v_mfma_f32_16x16x32_bf16 v[106:109], v[146:149], v[218:221], v[106:109]
	v_mfma_f32_16x16x32_bf16 v[94:97], v[138:141], v[226:229], v[94:97]
	v_mfma_f32_16x16x32_bf16 v[90:93], v[146:149], v[226:229], v[90:93]
	v_mfma_f32_16x16x32_bf16 v[78:81], v[138:141], v[234:237], v[78:81]
	v_mfma_f32_16x16x32_bf16 v[74:77], v[146:149], v[234:237], v[74:77]
	v_mfma_f32_16x16x32_bf16 v[118:121], v[150:153], v[166:169], v[118:121]
	v_mfma_f32_16x16x32_bf16 v[114:117], v[158:161], v[166:169], v[114:117]
	v_mfma_f32_16x16x32_bf16 v[102:105], v[150:153], v[214:217], v[102:105]
	v_mfma_f32_16x16x32_bf16 v[98:101], v[158:161], v[214:217], v[98:101]
	v_mfma_f32_16x16x32_bf16 v[86:89], v[150:153], v[222:225], v[86:89]
	v_mfma_f32_16x16x32_bf16 v[82:85], v[158:161], v[222:225], v[82:85]
	v_mfma_f32_16x16x32_bf16 v[70:73], v[150:153], v[230:233], v[70:73]
	v_mfma_f32_16x16x32_bf16 v[66:69], v[158:161], v[230:233], v[66:69]
	v_mfma_f32_16x16x32_bf16 v[118:121], v[154:157], v[210:213], v[118:121]
	v_mfma_f32_16x16x32_bf16 v[114:117], v[162:165], v[210:213], v[114:117]
	v_mfma_f32_16x16x32_bf16 v[102:105], v[154:157], v[218:221], v[102:105]
	v_mfma_f32_16x16x32_bf16 v[98:101], v[162:165], v[218:221], v[98:101]
	v_mfma_f32_16x16x32_bf16 v[86:89], v[154:157], v[226:229], v[86:89]
	v_mfma_f32_16x16x32_bf16 v[82:85], v[162:165], v[226:229], v[82:85]
	v_mfma_f32_16x16x32_bf16 v[70:73], v[154:157], v[234:237], v[70:73]
	v_mfma_f32_16x16x32_bf16 v[66:69], v[162:165], v[234:237], v[66:69]
	s_barrier
	ds_read_b128 v[166:169], v203 offset:49152
	ds_read_b128 v[210:213], v203 offset:50176
	ds_read_b128 v[214:217], v203 offset:51200
	ds_read_b128 v[218:221], v203 offset:52224
	ds_read_b128 v[222:225], v203 offset:53248
	ds_read_b128 v[226:229], v203 offset:54272
	ds_read_b128 v[230:233], v203 offset:55296
	ds_read_b128 v[234:237], v203 offset:56320
	s_add_u32 s72, s70, 0x80
	s_addc_u32 s73, s71, 0
	s_mov_b32 m0, s33
	s_nop 0
	global_load_lds_dwordx4 v172, s[72:73]
	s_add_u32 s70, s70, 0x100080
	s_mov_b32 m0, s35
	s_nop 0
	global_load_lds_dwordx4 v174, s[72:73]
	s_addc_u32 s71, s71, 0
	s_mov_b32 m0, s75
	s_nop 0
	global_load_lds_dwordx4 v172, s[70:71]
	s_mov_b32 m0, s76
	s_nop 0
	global_load_lds_dwordx4 v174, s[70:71]
	s_mov_b32 m0, s67
	s_nop 0
	global_load_lds_dwordx4 v1, s[68:69]
	s_mov_b32 m0, s74
	s_nop 0
	global_load_lds_dwordx4 v173, s[68:69]
	s_waitcnt vmcnt(8) lgkmcnt(0)
	s_barrier
	v_mfma_f32_16x16x32_bf16 v[62:65], v[134:137], v[166:169], v[62:65]
	v_mfma_f32_16x16x32_bf16 v[58:61], v[142:145], v[166:169], v[58:61]
	v_mfma_f32_16x16x32_bf16 v[46:49], v[134:137], v[214:217], v[46:49]
	v_mfma_f32_16x16x32_bf16 v[42:45], v[142:145], v[214:217], v[42:45]
	v_mfma_f32_16x16x32_bf16 v[30:33], v[134:137], v[222:225], v[30:33]
	v_mfma_f32_16x16x32_bf16 v[26:29], v[142:145], v[222:225], v[26:29]
	v_mfma_f32_16x16x32_bf16 v[14:17], v[134:137], v[230:233], v[14:17]
	v_mfma_f32_16x16x32_bf16 v[10:13], v[142:145], v[230:233], v[10:13]
	v_mfma_f32_16x16x32_bf16 v[62:65], v[138:141], v[210:213], v[62:65]
	v_mfma_f32_16x16x32_bf16 v[58:61], v[146:149], v[210:213], v[58:61]
	v_mfma_f32_16x16x32_bf16 v[46:49], v[138:141], v[218:221], v[46:49]
	v_mfma_f32_16x16x32_bf16 v[42:45], v[146:149], v[218:221], v[42:45]
	v_mfma_f32_16x16x32_bf16 v[30:33], v[138:141], v[226:229], v[30:33]
	v_mfma_f32_16x16x32_bf16 v[26:29], v[146:149], v[226:229], v[26:29]
	v_mfma_f32_16x16x32_bf16 v[14:17], v[138:141], v[234:237], v[14:17]
	v_mfma_f32_16x16x32_bf16 v[10:13], v[146:149], v[234:237], v[10:13]
	v_mfma_f32_16x16x32_bf16 v[54:57], v[150:153], v[166:169], v[54:57]
	v_mfma_f32_16x16x32_bf16 v[50:53], v[158:161], v[166:169], v[50:53]
	v_mfma_f32_16x16x32_bf16 v[38:41], v[150:153], v[214:217], v[38:41]
	v_mfma_f32_16x16x32_bf16 v[34:37], v[158:161], v[214:217], v[34:37]
	v_mfma_f32_16x16x32_bf16 v[22:25], v[150:153], v[222:225], v[22:25]
	v_mfma_f32_16x16x32_bf16 v[18:21], v[158:161], v[222:225], v[18:21]
	v_mfma_f32_16x16x32_bf16 v[6:9], v[150:153], v[230:233], v[6:9]
	v_mfma_f32_16x16x32_bf16 v[2:5], v[158:161], v[230:233], v[2:5]
	v_mfma_f32_16x16x32_bf16 v[54:57], v[154:157], v[210:213], v[54:57]
	v_mfma_f32_16x16x32_bf16 v[50:53], v[162:165], v[210:213], v[50:53]
	v_mfma_f32_16x16x32_bf16 v[38:41], v[154:157], v[218:221], v[38:41]
	v_mfma_f32_16x16x32_bf16 v[34:37], v[162:165], v[218:221], v[34:37]
	v_mfma_f32_16x16x32_bf16 v[22:25], v[154:157], v[226:229], v[22:25]
	v_mfma_f32_16x16x32_bf16 v[18:21], v[162:165], v[226:229], v[18:21]
	v_mfma_f32_16x16x32_bf16 v[6:9], v[154:157], v[234:237], v[6:9]
	v_mfma_f32_16x16x32_bf16 v[2:5], v[162:165], v[234:237], v[2:5]
	s_barrier
	s_add_i32 s85, s85, 2
	s_add_u32 s25, s25, 0x100
	s_addc_u32 s39, s39, 0
	s_add_u32 s59, s59, 0x100
	s_addc_u32 s84, s84, 0
	s_add_u32 s6, s6, 0x100
	s_addc_u32 s7, s7, 0
	s_cmp_gt_u32 s85, 61
	s_cbranch_scc0 .LBB0_892

; __device__ __forceinline__ unsigned cvt_pk_bf16(float lo, float hi) { unsigned r; asm volatile("v_cvt_pk_bf16_f32 %0, %1, %2" : "=v"(r) : "v"(lo), "v"(hi)); return r; }
; __device__ __forceinline__ float bf_lo(unsigned w) { return __uint_as_float(w << 16); }
; __device__ __forceinline__ float bf_hi(unsigned w) { return __uint_as_float(w & 0xffff0000u); }
;     __device__ __forceinline__ void operator()(EPI_ARGS) const {
;         const int row0 = u.pm * BM + wr * 64 + fr, col0 = u.pn * BM + wc * 32 + 8 * fq;
;         float ssv[8], mxv[8];
; #pragma unroll
;         for (int ai = 0; ai < 2; ++ai) {
;             f32x4 r0[4][2], r1[4][2];
; #pragma unroll
;             for (int m = 0; m < 4; ++m)
; #pragma unroll
;                 for (int bj = 0; bj < 2; ++bj) { const size_t off = (size_t)(row0 + ai * HALF + m * 16) * ldc + col0 + bj * HALF;
;                     if (RES_BF16) { const u32x4 rw = *(const u32x4*)((const bf16*)resid + off); r0[m][bj] = __builtin_bit_cast(f32x4, rw); }
;                     else { r0[m][bj] = *(const f32x4*)((const float*)resid + off); r1[m][bj] = *(const f32x4*)((const float*)resid + off + 4); } }
; #pragma unroll
;             for (int m = 0; m < 4; ++m) { const int row = row0 + ai * HALF + m * 16; const size_t off = (size_t)row * ldc + col0; float ss = 0.f, mx = 0.f;
; #pragma unroll
;                 for (int bj = 0; bj < 2; ++bj) {
;                     f32x4 a0, a1;
;                     if (RES_BF16) { const u32x4 rw = __builtin_bit_cast(u32x4, r0[m][bj]); a0 = (f32x4){bf_lo(rw.x), bf_hi(rw.x), bf_lo(rw.y), bf_hi(rw.y)}; a1 = (f32x4){bf_lo(rw.z), bf_hi(rw.z), bf_lo(rw.w), bf_hi(rw.w)};
;                         if (RES_SCALE) { const float rf = rfac[row]; a0 = a0 * rf; a1 = a1 * rf; } }
;                     else { a0 = r0[m][bj]; a1 = r1[m][bj]; }
;                     const f32x4 v0 = acc[ai][bj][m][0] + a0, v1 = acc[ai][bj][m][1] + a1;
;                     u32x4 w; w.x = cvt_pk_bf16(v0[0], v0[1]); w.y = cvt_pk_bf16(v0[2], v0[3]); w.z = cvt_pk_bf16(v1[0], v1[1]); w.w = cvt_pk_bf16(v1[2], v1[3]); *(u32x4*)(ob + off + bj * HALF) = w;
;                     ss += (v0[0] * v0[0] + v0[1] * v0[1]) + (v0[2] * v0[2] + v0[3] * v0[3]) + (v1[0] * v1[0] + v1[1] * v1[1]) + (v1[2] * v1[2] + v1[3] * v1[3]);
.LBB0_1005:
	s_nop 7
	v_lshl_add_u32 v245, s72, 8, v181
	v_mul_u32_u24_e32 v245, 0x2080, v245
	v_lshl_or_b32 v246, s70, 8, v182
	v_lshl_add_u32 v245, v246, 1, v245
	global_load_dwordx4 v[130:133], v245, s[98:99]
	global_load_dwordx4 v[134:137], v245, s[98:99] offset:256
	v_add_u32_e32 v246, 0x20800, v245
	global_load_dwordx4 v[138:141], v246, s[98:99]
	global_load_dwordx4 v[142:145], v246, s[98:99] offset:256
	v_add_u32_e32 v255, 0x41000, v245
	global_load_dwordx4 v[146:149], v255, s[98:99]
	global_load_dwordx4 v[150:153], v255, s[98:99] offset:256
	v_add_u32_e32 v246, 0x61800, v245
	global_load_dwordx4 v[154:157], v246, s[98:99]
	global_load_dwordx4 v[162:165], v246, s[98:99] offset:256
	v_add_u32_e32 v255, 0x104000, v245
	global_load_dwordx4 v[166:169], v255, s[98:99]
	global_load_dwordx4 v[170:173], v255, s[98:99] offset:256
	v_add_u32_e32 v246, 0x124800, v245
	global_load_dwordx4 v[190:193], v246, s[98:99]
	global_load_dwordx4 v[194:197], v246, s[98:99] offset:256
	v_add_u32_e32 v255, 0x145000, v245
	global_load_dwordx4 v[198:201], v255, s[98:99]
	global_load_dwordx4 v[202:205], v255, s[98:99] offset:256
	v_add_u32_e32 v246, 0x165800, v245
	global_load_dwordx4 v[206:209], v246, s[98:99]
	global_load_dwordx4 v[210:213], v246, s[98:99] offset:256
	s_waitcnt vmcnt(15)
	v_lshlrev_b32_e32 v248, 16, v130
	v_and_b32_e32 v249, 0xffff0000, v130
	v_lshlrev_b32_e32 v250, 16, v131
	v_and_b32_e32 v251, 0xffff0000, v131
	v_pk_add_f32 v[126:127], v[126:127], v[248:249]
	v_pk_add_f32 v[128:129], v[128:129], v[250:251]
	v_lshlrev_b32_e32 v248, 16, v132
	v_and_b32_e32 v249, 0xffff0000, v132
	v_lshlrev_b32_e32 v250, 16, v133
	v_and_b32_e32 v251, 0xffff0000, v133
	v_pk_add_f32 v[122:123], v[122:123], v[248:249]
	v_pk_add_f32 v[124:125], v[124:125], v[250:251]
	v_cvt_pk_bf16_f32 v130, v126, v127
	v_cvt_pk_bf16_f32 v131, v128, v129
	v_cvt_pk_bf16_f32 v132, v122, v123
	v_cvt_pk_bf16_f32 v133, v124, v125
	global_store_dwordx4 v245, v[130:133], s[100:101]
	v_mul_f32_e32 v247, v126, v126
	v_fmac_f32_e32 v247, v127, v127
	v_fmac_f32_e32 v247, v128, v128
	v_fmac_f32_e32 v247, v129, v129
	v_mul_f32_e32 v254, v122, v122
	v_fmac_f32_e32 v254, v123, v123
	v_fmac_f32_e32 v254, v124, v124
	v_fmac_f32_e32 v254, v125, v125
	v_max3_f32 v252, |v126|, |v127|, |v128|
	v_max3_f32 v252, |v129|, |v122|, v252
	v_max3_f32 v252, |v123|, |v124|, v252
	v_max_f32_e64 v252, |v125|, v252
	s_waitcnt vmcnt(15)
	v_lshlrev_b32_e32 v248, 16, v134
	v_and_b32_e32 v249, 0xffff0000, v134
	v_lshlrev_b32_e32 v250, 16, v135
	v_and_b32_e32 v251, 0xffff0000, v135
	v_pk_add_f32 v[118:119], v[118:119], v[248:249]
	v_pk_add_f32 v[120:121], v[120:121], v[250:251]
	v_lshlrev_b32_e32 v248, 16, v136
	v_and_b32_e32 v249, 0xffff0000, v136
	v_lshlrev_b32_e32 v250, 16, v137
	v_and_b32_e32 v251, 0xffff0000, v137
	v_pk_add_f32 v[114:115], v[114:115], v[248:249]
	v_pk_add_f32 v[116:117], v[116:117], v[250:251]
	v_cvt_pk_bf16_f32 v134, v118, v119
	v_cvt_pk_bf16_f32 v135, v120, v121
	v_cvt_pk_bf16_f32 v136, v114, v115
	v_cvt_pk_bf16_f32 v137, v116, v117
	global_store_dwordx4 v245, v[134:137], s[100:101] offset:256
	v_fmac_f32_e32 v247, v118, v118
	v_fmac_f32_e32 v247, v119, v119
	v_fmac_f32_e32 v247, v120, v120
	v_fmac_f32_e32 v247, v121, v121
	v_fmac_f32_e32 v254, v114, v114
	v_fmac_f32_e32 v254, v115, v115
	v_fmac_f32_e32 v254, v116, v116
	v_fmac_f32_e32 v254, v117, v117
	v_max3_f32 v252, |v118|, |v119|, v252
	v_max_f32_e64 v252, |v120|, v252
	v_max3_f32 v252, |v121|, |v114|, v252
	v_max3_f32 v252, |v115|, |v116|, v252
	v_max_f32_e64 v252, |v117|, v252
	v_add_f32_e32 v126, v247, v254
	v_mov_b32_e32 v128, v252
	s_waitcnt vmcnt(15)
	v_lshlrev_b32_e32 v248, 16, v138
	v_and_b32_e32 v249, 0xffff0000, v138
	v_lshlrev_b32_e32 v250, 16, v139
	v_and_b32_e32 v251, 0xffff0000, v139
	v_pk_add_f32 v[110:111], v[110:111], v[248:249]
	v_pk_add_f32 v[112:113], v[112:113], v[250:251]
	v_lshlrev_b32_e32 v248, 16, v140
	v_and_b32_e32 v249, 0xffff0000, v140
	v_lshlrev_b32_e32 v250, 16, v141
	v_and_b32_e32 v251, 0xffff0000, v141
	v_pk_add_f32 v[106:107], v[106:107], v[248:249]
	v_pk_add_f32 v[108:109], v[108:109], v[250:251]
	v_cvt_pk_bf16_f32 v138, v110, v111
	v_cvt_pk_bf16_f32 v139, v112, v113
	v_cvt_pk_bf16_f32 v140, v106, v107
	v_cvt_pk_bf16_f32 v141, v108, v109
	v_add_u32_e32 v246, 0x20800, v245
	global_store_dwordx4 v246, v[138:141], s[100:101]
	v_mul_f32_e32 v247, v110, v110
	v_fmac_f32_e32 v247, v111, v111
	v_fmac_f32_e32 v247, v112, v112
	v_fmac_f32_e32 v247, v113, v113
	v_mul_f32_e32 v254, v106, v106
	v_fmac_f32_e32 v254, v107, v107
	v_fmac_f32_e32 v254, v108, v108
	v_fmac_f32_e32 v254, v109, v109
	v_max3_f32 v252, |v110|, |v111|, |v112|
	v_max3_f32 v252, |v113|, |v106|, v252
	v_max3_f32 v252, |v107|, |v108|, v252
	v_max_f32_e64 v252, |v109|, v252
	s_waitcnt vmcnt(15)
	v_lshlrev_b32_e32 v248, 16, v142
	v_and_b32_e32 v249, 0xffff0000, v142
	v_lshlrev_b32_e32 v250, 16, v143
	v_and_b32_e32 v251, 0xffff0000, v143
	v_pk_add_f32 v[102:103], v[102:103], v[248:249]
	v_pk_add_f32 v[104:105], v[104:105], v[250:251]
	v_lshlrev_b32_e32 v248, 16, v144
	v_and_b32_e32 v249, 0xffff0000, v144
	v_lshlrev_b32_e32 v250, 16, v145
	v_and_b32_e32 v251, 0xffff0000, v145
	v_pk_add_f32 v[98:99], v[98:99], v[248:249]
	v_pk_add_f32 v[100:101], v[100:101], v[250:251]
	v_cvt_pk_bf16_f32 v142, v102, v103
	v_cvt_pk_bf16_f32 v143, v104, v105
	v_cvt_pk_bf16_f32 v144, v98, v99
	v_cvt_pk_bf16_f32 v145, v100, v101
	v_add_u32_e32 v255, 0x20800, v245
	global_store_dwordx4 v255, v[142:145], s[100:101] offset:256
	v_fmac_f32_e32 v247, v102, v102
	v_fmac_f32_e32 v247, v103, v103
	v_fmac_f32_e32 v247, v104, v104
	v_fmac_f32_e32 v247, v105, v105
	v_fmac_f32_e32 v254, v98, v98
	v_fmac_f32_e32 v254, v99, v99
	v_fmac_f32_e32 v254, v100, v100
	v_fmac_f32_e32 v254, v101, v101
	v_max3_f32 v252, |v102|, |v103|, v252
	v_max_f32_e64 v252, |v104|, v252
	v_max3_f32 v252, |v105|, |v98|, v252
	v_max3_f32 v252, |v99|, |v100|, v252
	v_max_f32_e64 v252, |v101|, v252
	v_add_f32_e32 v110, v247, v254
	v_mov_b32_e32 v112, v252
	s_waitcnt vmcnt(15)
; __device__ __forceinline__ unsigned cvt_pk_bf16(float lo, float hi) { unsigned r; asm volatile("v_cvt_pk_bf16_f32 %0, %1, %2" : "=v"(r) : "v"(lo), "v"(hi)); return r; }
; __device__ __forceinline__ float bf_lo(unsigned w) { return __uint_as_float(w << 16); }
; __device__ __forceinline__ float bf_hi(unsigned w) { return __uint_as_float(w & 0xffff0000u); }
;     __device__ __forceinline__ void operator()(EPI_ARGS) const {
;     ...
;             for (int m = 0; m < 4; ++m) { const int row = row0 + ai * HALF + m * 16; const size_t off = (size_t)row * ldc + col0; float ss = 0.f, mx = 0.f;
; #pragma unroll
;                 for (int bj = 0; bj < 2; ++bj) {
;                     f32x4 a0, a1;
;                     if (RES_BF16) { const u32x4 rw = __builtin_bit_cast(u32x4, r0[m][bj]); a0 = (f32x4){bf_lo(rw.x), bf_hi(rw.x), bf_lo(rw.y), bf_hi(rw.y)}; a1 = (f32x4){bf_lo(rw.z), bf_hi(rw.z), bf_lo(rw.w), bf_hi(rw.w)};
;                         if (RES_SCALE) { const float rf = rfac[row]; a0 = a0 * rf; a1 = a1 * rf; } }
;                     else { a0 = r0[m][bj]; a1 = r1[m][bj]; }
;                     const f32x4 v0 = acc[ai][bj][m][0] + a0, v1 = acc[ai][bj][m][1] + a1;
;                     u32x4 w; w.x = cvt_pk_bf16(v0[0], v0[1]); w.y = cvt_pk_bf16(v0[2], v0[3]); w.z = cvt_pk_bf16(v1[0], v1[1]); w.w = cvt_pk_bf16(v1[2], v1[3]); *(u32x4*)(ob + off + bj * HALF) = w;
;                     ss += (v0[0] * v0[0] + v0[1] * v0[1]) + (v0[2] * v0[2] + v0[3] * v0[3]) + (v1[0] * v1[0] + v1[1] * v1[1]) + (v1[2] * v1[2] + v1[3] * v1[3]);
;                     if (rowmax) mx = fmaxf(mx, fmaxf(fmaxf(fmaxf(fabsf(v0[0]), fabsf(v0[1])), fmaxf(fabsf(v0[2]), fabsf(v0[3]))), fmaxf(fmaxf(fabsf(v1[0]), fabsf(v1[1])), fmaxf(fabsf(v1[2]), fabsf(v1[3]))))); }
	v_lshlrev_b32_e32 v248, 16, v146
	v_and_b32_e32 v249, 0xffff0000, v146
	v_lshlrev_b32_e32 v250, 16, v147
	v_and_b32_e32 v251, 0xffff0000, v147
	v_pk_add_f32 v[94:95], v[94:95], v[248:249]
	v_pk_add_f32 v[96:97], v[96:97], v[250:251]
	v_lshlrev_b32_e32 v248, 16, v148
	v_and_b32_e32 v249, 0xffff0000, v148
	v_lshlrev_b32_e32 v250, 16, v149
	v_and_b32_e32 v251, 0xffff0000, v149
	v_pk_add_f32 v[90:91], v[90:91], v[248:249]
	v_pk_add_f32 v[92:93], v[92:93], v[250:251]
	v_cvt_pk_bf16_f32 v146, v94, v95
	v_cvt_pk_bf16_f32 v147, v96, v97
	v_cvt_pk_bf16_f32 v148, v90, v91
	v_cvt_pk_bf16_f32 v149, v92, v93
	v_add_u32_e32 v246, 0x41000, v245
	global_store_dwordx4 v246, v[146:149], s[100:101]
	v_mul_f32_e32 v247, v94, v94
	v_fmac_f32_e32 v247, v95, v95
	v_fmac_f32_e32 v247, v96, v96
	v_fmac_f32_e32 v247, v97, v97
	v_mul_f32_e32 v254, v90, v90
	v_fmac_f32_e32 v254, v91, v91
	v_fmac_f32_e32 v254, v92, v92
	v_fmac_f32_e32 v254, v93, v93
	v_max3_f32 v252, |v94|, |v95|, |v96|
	v_max3_f32 v252, |v97|, |v90|, v252
	v_max3_f32 v252, |v91|, |v92|, v252
	v_max_f32_e64 v252, |v93|, v252
	s_waitcnt vmcnt(15)
	v_lshlrev_b32_e32 v248, 16, v150
	v_and_b32_e32 v249, 0xffff0000, v150
	v_lshlrev_b32_e32 v250, 16, v151
	v_and_b32_e32 v251, 0xffff0000, v151
	v_pk_add_f32 v[86:87], v[86:87], v[248:249]
	v_pk_add_f32 v[88:89], v[88:89], v[250:251]
	v_lshlrev_b32_e32 v248, 16, v152
	v_and_b32_e32 v249, 0xffff0000, v152
	v_lshlrev_b32_e32 v250, 16, v153
	v_and_b32_e32 v251, 0xffff0000, v153
	v_pk_add_f32 v[82:83], v[82:83], v[248:249]
	v_pk_add_f32 v[84:85], v[84:85], v[250:251]
	v_cvt_pk_bf16_f32 v150, v86, v87
	v_cvt_pk_bf16_f32 v151, v88, v89
	v_cvt_pk_bf16_f32 v152, v82, v83
	v_cvt_pk_bf16_f32 v153, v84, v85
	v_add_u32_e32 v255, 0x41000, v245
	global_store_dwordx4 v255, v[150:153], s[100:101] offset:256
	v_fmac_f32_e32 v247, v86, v86
	v_fmac_f32_e32 v247, v87, v87
	v_fmac_f32_e32 v247, v88, v88
	v_fmac_f32_e32 v247, v89, v89
	v_fmac_f32_e32 v254, v82, v82
	v_fmac_f32_e32 v254, v83, v83
	v_fmac_f32_e32 v254, v84, v84
	v_fmac_f32_e32 v254, v85, v85
	v_max3_f32 v252, |v86|, |v87|, v252
	v_max_f32_e64 v252, |v88|, v252
	v_max3_f32 v252, |v89|, |v82|, v252
	v_max3_f32 v252, |v83|, |v84|, v252
	v_max_f32_e64 v252, |v85|, v252
	v_add_f32_e32 v94, v247, v254
	v_mov_b32_e32 v96, v252
	s_waitcnt vmcnt(15)
	v_lshlrev_b32_e32 v248, 16, v154
	v_and_b32_e32 v249, 0xffff0000, v154
	v_lshlrev_b32_e32 v250, 16, v155
	v_and_b32_e32 v251, 0xffff0000, v155
	v_pk_add_f32 v[78:79], v[78:79], v[248:249]
	v_pk_add_f32 v[80:81], v[80:81], v[250:251]
	v_lshlrev_b32_e32 v248, 16, v156
	v_and_b32_e32 v249, 0xffff0000, v156
	v_lshlrev_b32_e32 v250, 16, v157
	v_and_b32_e32 v251, 0xffff0000, v157
	v_pk_add_f32 v[74:75], v[74:75], v[248:249]
	v_pk_add_f32 v[76:77], v[76:77], v[250:251]
	v_cvt_pk_bf16_f32 v154, v78, v79
	v_cvt_pk_bf16_f32 v155, v80, v81
	v_cvt_pk_bf16_f32 v156, v74, v75
	v_cvt_pk_bf16_f32 v157, v76, v77
	v_add_u32_e32 v246, 0x61800, v245
	global_store_dwordx4 v246, v[154:157], s[100:101]
	v_mul_f32_e32 v247, v78, v78
	v_fmac_f32_e32 v247, v79, v79
	v_fmac_f32_e32 v247, v80, v80
	v_fmac_f32_e32 v247, v81, v81
	v_mul_f32_e32 v254, v74, v74
	v_fmac_f32_e32 v254, v75, v75
	v_fmac_f32_e32 v254, v76, v76
	v_fmac_f32_e32 v254, v77, v77
	v_max3_f32 v252, |v78|, |v79|, |v80|
	v_max3_f32 v252, |v81|, |v74|, v252
	v_max3_f32 v252, |v75|, |v76|, v252
	v_max_f32_e64 v252, |v77|, v252
	s_waitcnt vmcnt(15)
	v_lshlrev_b32_e32 v248, 16, v162
	v_and_b32_e32 v249, 0xffff0000, v162
	v_lshlrev_b32_e32 v250, 16, v163
	v_and_b32_e32 v251, 0xffff0000, v163
	v_pk_add_f32 v[70:71], v[70:71], v[248:249]
	v_pk_add_f32 v[72:73], v[72:73], v[250:251]
	v_lshlrev_b32_e32 v248, 16, v164
	v_and_b32_e32 v249, 0xffff0000, v164
	v_lshlrev_b32_e32 v250, 16, v165
	v_and_b32_e32 v251, 0xffff0000, v165
	v_pk_add_f32 v[66:67], v[66:67], v[248:249]
	v_pk_add_f32 v[68:69], v[68:69], v[250:251]
	v_cvt_pk_bf16_f32 v162, v70, v71
	v_cvt_pk_bf16_f32 v163, v72, v73
	v_cvt_pk_bf16_f32 v164, v66, v67
	v_cvt_pk_bf16_f32 v165, v68, v69
	v_add_u32_e32 v255, 0x61800, v245
	global_store_dwordx4 v255, v[162:165], s[100:101] offset:256
	v_fmac_f32_e32 v247, v70, v70
	v_fmac_f32_e32 v247, v71, v71
	v_fmac_f32_e32 v247, v72, v72
	v_fmac_f32_e32 v247, v73, v73
	v_fmac_f32_e32 v254, v66, v66
	v_fmac_f32_e32 v254, v67, v67
	v_fmac_f32_e32 v254, v68, v68
	v_fmac_f32_e32 v254, v69, v69
	v_max3_f32 v252, |v70|, |v71|, v252
	v_max_f32_e64 v252, |v72|, v252
	v_max3_f32 v252, |v73|, |v66|, v252
	v_max3_f32 v252, |v67|, |v68|, v252
	v_max_f32_e64 v252, |v69|, v252
	v_add_f32_e32 v78, v247, v254
	v_mov_b32_e32 v80, v252
	s_waitcnt vmcnt(15)
	v_lshlrev_b32_e32 v248, 16, v166
	v_and_b32_e32 v249, 0xffff0000, v166
	v_lshlrev_b32_e32 v250, 16, v167
	v_and_b32_e32 v251, 0xffff0000, v167
	v_pk_add_f32 v[62:63], v[62:63], v[248:249]
	v_pk_add_f32 v[64:65], v[64:65], v[250:251]
	v_lshlrev_b32_e32 v248, 16, v168
	v_and_b32_e32 v249, 0xffff0000, v168
	v_lshlrev_b32_e32 v250, 16, v169
	v_and_b32_e32 v251, 0xffff0000, v169
	v_pk_add_f32 v[58:59], v[58:59], v[248:249]
	v_pk_add_f32 v[60:61], v[60:61], v[250:251]
	v_cvt_pk_bf16_f32 v166, v62, v63
	v_cvt_pk_bf16_f32 v167, v64, v65
	v_cvt_pk_bf16_f32 v168, v58, v59
	v_cvt_pk_bf16_f32 v169, v60, v61
	v_add_u32_e32 v246, 0x104000, v245
	global_store_dwordx4 v246, v[166:169], s[100:101]
	v_mul_f32_e32 v247, v62, v62
	v_fmac_f32_e32 v247, v63, v63
	v_fmac_f32_e32 v247, v64, v64
	v_fmac_f32_e32 v247, v65, v65
	v_mul_f32_e32 v254, v58, v58
	v_fmac_f32_e32 v254, v59, v59
	v_fmac_f32_e32 v254, v60, v60
	v_fmac_f32_e32 v254, v61, v61
	v_max3_f32 v252, |v62|, |v63|, |v64|
	v_max3_f32 v252, |v65|, |v58|, v252
	v_max3_f32 v252, |v59|, |v60|, v252
	v_max_f32_e64 v252, |v61|, v252
	s_waitcnt vmcnt(15)
; __device__ __forceinline__ unsigned cvt_pk_bf16(float lo, float hi) { unsigned r; asm volatile("v_cvt_pk_bf16_f32 %0, %1, %2" : "=v"(r) : "v"(lo), "v"(hi)); return r; }
; __device__ __forceinline__ float bf_lo(unsigned w) { return __uint_as_float(w << 16); }
; __device__ __forceinline__ float bf_hi(unsigned w) { return __uint_as_float(w & 0xffff0000u); }
;     __device__ __forceinline__ void operator()(EPI_ARGS) const {
;     ...
;             for (int m = 0; m < 4; ++m) { const int row = row0 + ai * HALF + m * 16; const size_t off = (size_t)row * ldc + col0; float ss = 0.f, mx = 0.f;
; #pragma unroll
;                 for (int bj = 0; bj < 2; ++bj) {
;                     f32x4 a0, a1;
;                     if (RES_BF16) { const u32x4 rw = __builtin_bit_cast(u32x4, r0[m][bj]); a0 = (f32x4){bf_lo(rw.x), bf_hi(rw.x), bf_lo(rw.y), bf_hi(rw.y)}; a1 = (f32x4){bf_lo(rw.z), bf_hi(rw.z), bf_lo(rw.w), bf_hi(rw.w)};
;                         if (RES_SCALE) { const float rf = rfac[row]; a0 = a0 * rf; a1 = a1 * rf; } }
;                     else { a0 = r0[m][bj]; a1 = r1[m][bj]; }
;                     const f32x4 v0 = acc[ai][bj][m][0] + a0, v1 = acc[ai][bj][m][1] + a1;
;                     u32x4 w; w.x = cvt_pk_bf16(v0[0], v0[1]); w.y = cvt_pk_bf16(v0[2], v0[3]); w.z = cvt_pk_bf16(v1[0], v1[1]); w.w = cvt_pk_bf16(v1[2], v1[3]); *(u32x4*)(ob + off + bj * HALF) = w;
;                     ss += (v0[0] * v0[0] + v0[1] * v0[1]) + (v0[2] * v0[2] + v0[3] * v0[3]) + (v1[0] * v1[0] + v1[1] * v1[1]) + (v1[2] * v1[2] + v1[3] * v1[3]);
;                     if (rowmax) mx = fmaxf(mx, fmaxf(fmaxf(fmaxf(fabsf(v0[0]), fabsf(v0[1])), fmaxf(fabsf(v0[2]), fabsf(v0[3]))), fmaxf(fmaxf(fabsf(v1[0]), fabsf(v1[1])), fmaxf(fabsf(v1[2]), fabsf(v1[3]))))); }
	v_lshlrev_b32_e32 v248, 16, v170
	v_and_b32_e32 v249, 0xffff0000, v170
	v_lshlrev_b32_e32 v250, 16, v171
	v_and_b32_e32 v251, 0xffff0000, v171
	v_pk_add_f32 v[54:55], v[54:55], v[248:249]
	v_pk_add_f32 v[56:57], v[56:57], v[250:251]
	v_lshlrev_b32_e32 v248, 16, v172
	v_and_b32_e32 v249, 0xffff0000, v172
	v_lshlrev_b32_e32 v250, 16, v173
	v_and_b32_e32 v251, 0xffff0000, v173
	v_pk_add_f32 v[50:51], v[50:51], v[248:249]
	v_pk_add_f32 v[52:53], v[52:53], v[250:251]
	v_cvt_pk_bf16_f32 v170, v54, v55
	v_cvt_pk_bf16_f32 v171, v56, v57
	v_cvt_pk_bf16_f32 v172, v50, v51
	v_cvt_pk_bf16_f32 v173, v52, v53
	v_add_u32_e32 v255, 0x104000, v245
	global_store_dwordx4 v255, v[170:173], s[100:101] offset:256
	v_fmac_f32_e32 v247, v54, v54
	v_fmac_f32_e32 v247, v55, v55
	v_fmac_f32_e32 v247, v56, v56
	v_fmac_f32_e32 v247, v57, v57
	v_fmac_f32_e32 v254, v50, v50
	v_fmac_f32_e32 v254, v51, v51
	v_fmac_f32_e32 v254, v52, v52
	v_fmac_f32_e32 v254, v53, v53
	v_max3_f32 v252, |v54|, |v55|, v252
	v_max_f32_e64 v252, |v56|, v252
	v_max3_f32 v252, |v57|, |v50|, v252
	v_max3_f32 v252, |v51|, |v52|, v252
	v_max_f32_e64 v252, |v53|, v252
	v_add_f32_e32 v62, v247, v254
	v_mov_b32_e32 v64, v252
	s_waitcnt vmcnt(15)
	v_lshlrev_b32_e32 v248, 16, v190
	v_and_b32_e32 v249, 0xffff0000, v190
	v_lshlrev_b32_e32 v250, 16, v191
	v_and_b32_e32 v251, 0xffff0000, v191
	v_pk_add_f32 v[46:47], v[46:47], v[248:249]
	v_pk_add_f32 v[48:49], v[48:49], v[250:251]
	v_lshlrev_b32_e32 v248, 16, v192
	v_and_b32_e32 v249, 0xffff0000, v192
	v_lshlrev_b32_e32 v250, 16, v193
	v_and_b32_e32 v251, 0xffff0000, v193
	v_pk_add_f32 v[42:43], v[42:43], v[248:249]
	v_pk_add_f32 v[44:45], v[44:45], v[250:251]
	v_cvt_pk_bf16_f32 v190, v46, v47
	v_cvt_pk_bf16_f32 v191, v48, v49
	v_cvt_pk_bf16_f32 v192, v42, v43
	v_cvt_pk_bf16_f32 v193, v44, v45
	v_add_u32_e32 v246, 0x124800, v245
	global_store_dwordx4 v246, v[190:193], s[100:101]
	v_mul_f32_e32 v247, v46, v46
	v_fmac_f32_e32 v247, v47, v47
	v_fmac_f32_e32 v247, v48, v48
	v_fmac_f32_e32 v247, v49, v49
	v_mul_f32_e32 v254, v42, v42
	v_fmac_f32_e32 v254, v43, v43
	v_fmac_f32_e32 v254, v44, v44
	v_fmac_f32_e32 v254, v45, v45
	v_max3_f32 v252, |v46|, |v47|, |v48|
	v_max3_f32 v252, |v49|, |v42|, v252
	v_max3_f32 v252, |v43|, |v44|, v252
	v_max_f32_e64 v252, |v45|, v252
	s_waitcnt vmcnt(15)
	v_lshlrev_b32_e32 v248, 16, v194
	v_and_b32_e32 v249, 0xffff0000, v194
	v_lshlrev_b32_e32 v250, 16, v195
	v_and_b32_e32 v251, 0xffff0000, v195
	v_pk_add_f32 v[38:39], v[38:39], v[248:249]
	v_pk_add_f32 v[40:41], v[40:41], v[250:251]
	v_lshlrev_b32_e32 v248, 16, v196
	v_and_b32_e32 v249, 0xffff0000, v196
	v_lshlrev_b32_e32 v250, 16, v197
	v_and_b32_e32 v251, 0xffff0000, v197
	v_pk_add_f32 v[34:35], v[34:35], v[248:249]
	v_pk_add_f32 v[36:37], v[36:37], v[250:251]
	v_cvt_pk_bf16_f32 v194, v38, v39
	v_cvt_pk_bf16_f32 v195, v40, v41
	v_cvt_pk_bf16_f32 v196, v34, v35
	v_cvt_pk_bf16_f32 v197, v36, v37
	v_add_u32_e32 v255, 0x124800, v245
	global_store_dwordx4 v255, v[194:197], s[100:101] offset:256
	v_fmac_f32_e32 v247, v38, v38
	v_fmac_f32_e32 v247, v39, v39
	v_fmac_f32_e32 v247, v40, v40
	v_fmac_f32_e32 v247, v41, v41
	v_fmac_f32_e32 v254, v34, v34
	v_fmac_f32_e32 v254, v35, v35
	v_fmac_f32_e32 v254, v36, v36
	v_fmac_f32_e32 v254, v37, v37
	v_max3_f32 v252, |v38|, |v39|, v252
	v_max_f32_e64 v252, |v40|, v252
	v_max3_f32 v252, |v41|, |v34|, v252
	v_max3_f32 v252, |v35|, |v36|, v252
	v_max_f32_e64 v252, |v37|, v252
	v_add_f32_e32 v46, v247, v254
	v_mov_b32_e32 v48, v252
	s_waitcnt vmcnt(15)
	v_lshlrev_b32_e32 v248, 16, v198
	v_and_b32_e32 v249, 0xffff0000, v198
	v_lshlrev_b32_e32 v250, 16, v199
	v_and_b32_e32 v251, 0xffff0000, v199
	v_pk_add_f32 v[30:31], v[30:31], v[248:249]
	v_pk_add_f32 v[32:33], v[32:33], v[250:251]
	v_lshlrev_b32_e32 v248, 16, v200
	v_and_b32_e32 v249, 0xffff0000, v200
	v_lshlrev_b32_e32 v250, 16, v201
	v_and_b32_e32 v251, 0xffff0000, v201
	v_pk_add_f32 v[26:27], v[26:27], v[248:249]
	v_pk_add_f32 v[28:29], v[28:29], v[250:251]
	v_cvt_pk_bf16_f32 v198, v30, v31
	v_cvt_pk_bf16_f32 v199, v32, v33
	v_cvt_pk_bf16_f32 v200, v26, v27
	v_cvt_pk_bf16_f32 v201, v28, v29
	v_add_u32_e32 v246, 0x145000, v245
	global_store_dwordx4 v246, v[198:201], s[100:101]
	v_mul_f32_e32 v247, v30, v30
	v_fmac_f32_e32 v247, v31, v31
	v_fmac_f32_e32 v247, v32, v32
	v_fmac_f32_e32 v247, v33, v33
	v_mul_f32_e32 v254, v26, v26
	v_fmac_f32_e32 v254, v27, v27
	v_fmac_f32_e32 v254, v28, v28
	v_fmac_f32_e32 v254, v29, v29
	v_max3_f32 v252, |v30|, |v31|, |v32|
	v_max3_f32 v252, |v33|, |v26|, v252
	v_max3_f32 v252, |v27|, |v28|, v252
	v_max_f32_e64 v252, |v29|, v252
	s_waitcnt vmcnt(15)
	v_lshlrev_b32_e32 v248, 16, v202
	v_and_b32_e32 v249, 0xffff0000, v202
	v_lshlrev_b32_e32 v250, 16, v203
	v_and_b32_e32 v251, 0xffff0000, v203
	v_pk_add_f32 v[22:23], v[22:23], v[248:249]
	v_pk_add_f32 v[24:25], v[24:25], v[250:251]
	v_lshlrev_b32_e32 v248, 16, v204
	v_and_b32_e32 v249, 0xffff0000, v204
	v_lshlrev_b32_e32 v250, 16, v205
	v_and_b32_e32 v251, 0xffff0000, v205
	v_pk_add_f32 v[18:19], v[18:19], v[248:249]
	v_pk_add_f32 v[20:21], v[20:21], v[250:251]
	v_cvt_pk_bf16_f32 v202, v22, v23
	v_cvt_pk_bf16_f32 v203, v24, v25
	v_cvt_pk_bf16_f32 v204, v18, v19
	v_cvt_pk_bf16_f32 v205, v20, v21
	v_add_u32_e32 v255, 0x145000, v245
	global_store_dwordx4 v255, v[202:205], s[100:101] offset:256
	v_fmac_f32_e32 v247, v22, v22
	v_fmac_f32_e32 v247, v23, v23
	v_fmac_f32_e32 v247, v24, v24
	v_fmac_f32_e32 v247, v25, v25
	v_fmac_f32_e32 v254, v18, v18
	v_fmac_f32_e32 v254, v19, v19
	v_fmac_f32_e32 v254, v20, v20
	v_fmac_f32_e32 v254, v21, v21
	v_max3_f32 v252, |v22|, |v23|, v252
	v_max_f32_e64 v252, |v24|, v252
	v_max3_f32 v252, |v25|, |v18|, v252
	v_max3_f32 v252, |v19|, |v20|, v252
	v_max_f32_e64 v252, |v21|, v252
	v_add_f32_e32 v30, v247, v254
	v_mov_b32_e32 v32, v252
	s_waitcnt vmcnt(15)
;     __device__ __forceinline__ void operator()(EPI_ARGS) const {
;     ...
;                 ss += __shfl_xor(ss, 16); ss += __shfl_xor(ss, 32); ssv[ai * 4 + m] = ss;
;                 if (rowmax) { mx = fmaxf(mx, __shfl_xor(mx, 16)); mx = fmaxf(mx, __shfl_xor(mx, 32)); } mxv[ai * 4 + m] = mx; }
;             asm volatile("" ::: "memory"); }
;         float s0 = 0.f, s1 = 0.f, m0 = 0.f, m1 = 0.f;
; #pragma unroll
;         for (int k = 0; k < 8; ++k) if ((k >> 1) == fq) { if (k & 1) { s1 = ssv[k]; m1 = mxv[k]; } else { s0 = ssv[k]; m0 = mxv[k]; } }
;         const int rq = row0 + (fq >> 1) * HALF + (fq & 1) * 32;
;         __hip_atomic_fetch_add(rowsq + rq, s0, __ATOMIC_RELAXED, __HIP_MEMORY_SCOPE_AGENT); __hip_atomic_fetch_add(rowsq + rq + 16, s1, __ATOMIC_RELAXED, __HIP_MEMORY_SCOPE_AGENT);
;         if (rowmax) { __hip_atomic_fetch_max(rowmax + rq, __float_as_uint(m0), __ATOMIC_RELAXED, __HIP_MEMORY_SCOPE_AGENT); __hip_atomic_fetch_max(rowmax + rq + 16, __float_as_uint(m1), __ATOMIC_RELAXED, __HIP_MEMORY_SCOPE_AGENT); }
	v_lshlrev_b32_e32 v248, 16, v206
	v_and_b32_e32 v249, 0xffff0000, v206
	v_lshlrev_b32_e32 v250, 16, v207
	v_and_b32_e32 v251, 0xffff0000, v207
	v_pk_add_f32 v[14:15], v[14:15], v[248:249]
	v_pk_add_f32 v[16:17], v[16:17], v[250:251]
	v_lshlrev_b32_e32 v248, 16, v208
	v_and_b32_e32 v249, 0xffff0000, v208
	v_lshlrev_b32_e32 v250, 16, v209
	v_and_b32_e32 v251, 0xffff0000, v209
	v_pk_add_f32 v[10:11], v[10:11], v[248:249]
	v_pk_add_f32 v[12:13], v[12:13], v[250:251]
	v_cvt_pk_bf16_f32 v206, v14, v15
	v_cvt_pk_bf16_f32 v207, v16, v17
	v_cvt_pk_bf16_f32 v208, v10, v11
	v_cvt_pk_bf16_f32 v209, v12, v13
	v_add_u32_e32 v246, 0x165800, v245
	global_store_dwordx4 v246, v[206:209], s[100:101]
	v_mul_f32_e32 v247, v14, v14
	v_fmac_f32_e32 v247, v15, v15
	v_fmac_f32_e32 v247, v16, v16
	v_fmac_f32_e32 v247, v17, v17
	v_mul_f32_e32 v254, v10, v10
	v_fmac_f32_e32 v254, v11, v11
	v_fmac_f32_e32 v254, v12, v12
	v_fmac_f32_e32 v254, v13, v13
	v_max3_f32 v252, |v14|, |v15|, |v16|
	v_max3_f32 v252, |v17|, |v10|, v252
	v_max3_f32 v252, |v11|, |v12|, v252
	v_max_f32_e64 v252, |v13|, v252
	s_waitcnt vmcnt(15)
	v_lshlrev_b32_e32 v248, 16, v210
	v_and_b32_e32 v249, 0xffff0000, v210
	v_lshlrev_b32_e32 v250, 16, v211
	v_and_b32_e32 v251, 0xffff0000, v211
	v_pk_add_f32 v[6:7], v[6:7], v[248:249]
	v_pk_add_f32 v[8:9], v[8:9], v[250:251]
	v_lshlrev_b32_e32 v248, 16, v212
	v_and_b32_e32 v249, 0xffff0000, v212
	v_lshlrev_b32_e32 v250, 16, v213
	v_and_b32_e32 v251, 0xffff0000, v213
	v_pk_add_f32 v[2:3], v[2:3], v[248:249]
	v_pk_add_f32 v[4:5], v[4:5], v[250:251]
	v_cvt_pk_bf16_f32 v210, v6, v7
	v_cvt_pk_bf16_f32 v211, v8, v9
	v_cvt_pk_bf16_f32 v212, v2, v3
	v_cvt_pk_bf16_f32 v213, v4, v5
	v_add_u32_e32 v255, 0x165800, v245
	global_store_dwordx4 v255, v[210:213], s[100:101] offset:256
	v_fmac_f32_e32 v247, v6, v6
	v_fmac_f32_e32 v247, v7, v7
	v_fmac_f32_e32 v247, v8, v8
	v_fmac_f32_e32 v247, v9, v9
	v_fmac_f32_e32 v254, v2, v2
	v_fmac_f32_e32 v254, v3, v3
	v_fmac_f32_e32 v254, v4, v4
	v_fmac_f32_e32 v254, v5, v5
	v_max3_f32 v252, |v6|, |v7|, v252
	v_max_f32_e64 v252, |v8|, v252
	v_max3_f32 v252, |v9|, |v2|, v252
	v_max3_f32 v252, |v3|, |v4|, v252
	v_max_f32_e64 v252, |v5|, v252
	v_add_f32_e32 v14, v247, v254
	v_mov_b32_e32 v16, v252
	v_and_b32_e32 v255, 63, v0
	v_xor_b32_e32 v252, 16, v255
	v_xor_b32_e32 v253, 32, v255
	v_lshlrev_b32_e32 v252, 2, v252
	v_lshlrev_b32_e32 v253, 2, v253
	ds_bpermute_b32 v127, v252, v126
	ds_bpermute_b32 v129, v252, v128
	ds_bpermute_b32 v111, v252, v110
	ds_bpermute_b32 v113, v252, v112
	ds_bpermute_b32 v95, v252, v94
	ds_bpermute_b32 v97, v252, v96
	ds_bpermute_b32 v79, v252, v78
	ds_bpermute_b32 v81, v252, v80
	ds_bpermute_b32 v63, v252, v62
	ds_bpermute_b32 v65, v252, v64
	ds_bpermute_b32 v47, v252, v46
	ds_bpermute_b32 v49, v252, v48
	ds_bpermute_b32 v31, v252, v30
	ds_bpermute_b32 v33, v252, v32
	ds_bpermute_b32 v15, v252, v14
	ds_bpermute_b32 v17, v252, v16
	s_waitcnt lgkmcnt(0)
	v_add_f32_e32 v126, v126, v127
	v_max_f32_e32 v128, v128, v129
	v_add_f32_e32 v110, v110, v111
	v_max_f32_e32 v112, v112, v113
	v_add_f32_e32 v94, v94, v95
	v_max_f32_e32 v96, v96, v97
	v_add_f32_e32 v78, v78, v79
	v_max_f32_e32 v80, v80, v81
	v_add_f32_e32 v62, v62, v63
	v_max_f32_e32 v64, v64, v65
	v_add_f32_e32 v46, v46, v47
	v_max_f32_e32 v48, v48, v49
	v_add_f32_e32 v30, v30, v31
	v_max_f32_e32 v32, v32, v33
	v_add_f32_e32 v14, v14, v15
	v_max_f32_e32 v16, v16, v17
	ds_bpermute_b32 v127, v253, v126
	ds_bpermute_b32 v129, v253, v128
	ds_bpermute_b32 v111, v253, v110
	ds_bpermute_b32 v113, v253, v112
	ds_bpermute_b32 v95, v253, v94
	ds_bpermute_b32 v97, v253, v96
	ds_bpermute_b32 v79, v253, v78
	ds_bpermute_b32 v81, v253, v80
	ds_bpermute_b32 v63, v253, v62
	ds_bpermute_b32 v65, v253, v64
	ds_bpermute_b32 v47, v253, v46
	ds_bpermute_b32 v49, v253, v48
	ds_bpermute_b32 v31, v253, v30
	ds_bpermute_b32 v33, v253, v32
	ds_bpermute_b32 v15, v253, v14
	ds_bpermute_b32 v17, v253, v16
	s_waitcnt lgkmcnt(0)
	v_add_f32_e32 v126, v126, v127
	v_max_f32_e32 v128, v128, v129
	v_add_f32_e32 v110, v110, v111
	v_max_f32_e32 v112, v112, v113
	v_add_f32_e32 v94, v94, v95
	v_max_f32_e32 v96, v96, v97
	v_add_f32_e32 v78, v78, v79
	v_max_f32_e32 v80, v80, v81
	v_add_f32_e32 v62, v62, v63
	v_max_f32_e32 v64, v64, v65
	v_add_f32_e32 v46, v46, v47
	v_max_f32_e32 v48, v48, v49
	v_add_f32_e32 v30, v30, v31
	v_max_f32_e32 v32, v32, v33
	v_add_f32_e32 v14, v14, v15
	v_max_f32_e32 v16, v16, v17
	v_cndmask_b32_e64 v248, 0, v126, s[2:3]
	v_cndmask_b32_e64 v249, 0, v110, s[2:3]
	v_cndmask_b32_e64 v248, v248, v94, s[4:5]
	v_cndmask_b32_e64 v249, v249, v78, s[4:5]
	v_cndmask_b32_e64 v248, v248, v62, s[6:7]
	v_cndmask_b32_e64 v249, v249, v46, s[6:7]
	v_cndmask_b32_e64 v248, v248, v30, s[8:9]
	v_cndmask_b32_e64 v249, v249, v14, s[8:9]
	v_lshl_add_u32 v250, s72, 8, v181
	v_add_u32_e32 v250, v180, v250
	v_lshlrev_b32_e32 v250, 2, v250
	global_atomic_add_f32 v250, v248, s[54:55]
	global_atomic_add_f32 v250, v249, s[54:55] offset:64
	v_cndmask_b32_e64 v247, 0, v128, s[2:3]
	v_cndmask_b32_e64 v254, 0, v112, s[2:3]
	v_cndmask_b32_e64 v247, v247, v96, s[4:5]
	v_cndmask_b32_e64 v254, v254, v80, s[4:5]
	v_cndmask_b32_e64 v247, v247, v64, s[6:7]
	v_cndmask_b32_e64 v254, v254, v48, s[6:7]
	v_cndmask_b32_e64 v247, v247, v32, s[8:9]
	v_cndmask_b32_e64 v254, v254, v16, s[8:9]
	global_atomic_umax v250, v247, s[56:57]
	global_atomic_umax v250, v254, s[56:57] offset:64
	s_and_b64 vcc, exec, s[10:11]
	s_mov_b64 s[10:11], -1
	s_cbranch_vccnz .LBB0_992
	s_andn2_b64 vcc, exec, s[0:1]
	s_cbranch_vccnz .LBB0_991
	s_barrier
	s_branch .LBB0_991
